# hand-scheduled GEMM K-loop (rotated barrier, SGPR-base addressing, spread LDS writes) in all four GEMM phases
# speedup vs baseline: 1.0714x; 1.0447x over previous
; #define G5_LOAD(k0)                                                                 \
;   {                                                                                 \
;     _Pragma("unroll") for (int i_ = 0; i_ < 4; ++i_) ra[i_] = ldg16(Ap + (size_t)(i_ * 64) * lda + (k0)); \
;     _Pragma("unroll") for (int i_ = 0; i_ < 4; ++i_) rb[i_] = ldg16(Bp + (size_t)(i_ * 64) * ldb + (k0)); \
;   }
; #define G5_STORE(s)                                                                 \
;   {                                                                                 \
;     _Pragma("unroll") for (int i_ = 0; i_ < 4; ++i_) *(u32x4*)(Sw + (s) * STG + i_ * 64 * GS) = ra[i_]; \
;     _Pragma("unroll") for (int i_ = 0; i_ < 4; ++i_) *(u32x4*)(Sw + (s) * STG + 256 * GS + i_ * 64 * GS) = rb[i_]; \
;   }
; template <typename Epi>
; DI void gemm_tile512(const u16* __restrict__ A, int lda, const u16* __restrict__ Bt, int ldb, int K, char* lds_all, Epi epi) {
;     ...
;   f32x16 acc[4][2];
; #pragma unroll
;   for (int i = 0; i < 4; ++i)
; #pragma unroll
;     for (int j = 0; j < 2; ++j) acc[i][j] = zero16();
;   const int lrow = tid >> 3, lcol = (tid & 7) * 8;
;   const u16* Ap = A + (size_t)lrow * lda + lcol;
;   const u16* Bp = Bt + (size_t)lrow * ldb + lcol;
;   u16* Sw = S0 + lrow * GS + lcol;
;   u32x4 ra[4], rb[4];
;     ...
;   const int nk = K >> 6;
;   __syncthreads();
;   G5_LOAD(0);
;   G5_STORE(0);
;   G5_LOAD(64);
;   __syncthreads();
;   for (int kt = 0; kt + 2 < nk; ++kt) {
;     const int cur = kt & 1;
;     G5_COMPUTE(cur);
;     G5_STORE(cur ^ 1);
;     G5_LOAD((kt + 2) << 6);
;     __syncthreads();
;   }
.LBB0_198:
	s_mul_i32 s6, s4, 0xffffffea
	s_lshl_b32 s11, s5, 9
	s_lshl_b32 s5, s16, 8
	s_add_i32 s6, s6, s16
	s_and_b32 s5, s5, 0x100
	s_or_b32 s17, s5, s11
	s_lshl_b32 s5, s6, 7
	s_and_b32 s18, s5, 0xffffff00
	s_mul_i32 s6, s17, 0x900
	v_readlane_b32 s7, v250, 46
	s_mul_hi_i32 s5, s17, 0x900
	s_add_u32 s6, s7, s6
	v_readlane_b32 s7, v250, 47
	s_addc_u32 s7, s7, s5
	s_mul_i32 s8, s18, 0x900
	s_mul_hi_i32 s5, s18, 0x900
	s_add_u32 s8, s2, s8
	s_addc_u32 s9, s3, s5
	s_mov_b64 s[98:99], s[6:7]
	s_mov_b64 s[100:101], s[8:9]
	v_lshrrev_b32_e32 v239, 3, v165
	v_and_b32_e32 v0, 7, v165
	v_mul_u32_u24_e32 v206, 0x900, v239
	v_lshl_add_u32 v206, v0, 4, v206
	v_add_u32_e32 v207, 0x24000, v206
	v_add_u32_e32 v208, 0x48000, v206
	v_add_u32_e32 v238, 0x6c000, v206
	v_mul_u32_u24_e32 v180, 0x90, v239
	v_lshl_add_u32 v180, v0, 4, v180
	global_load_dwordx4 v[2:5], v206, s[98:99]
	global_load_dwordx4 v[6:9], v207, s[98:99]
	global_load_dwordx4 v[10:13], v208, s[98:99]
	global_load_dwordx4 v[14:17], v238, s[98:99]
	global_load_dwordx4 v[18:21], v206, s[100:101]
	global_load_dwordx4 v[22:25], v207, s[100:101]
	global_load_dwordx4 v[26:29], v208, s[100:101]
	global_load_dwordx4 v[30:33], v238, s[100:101]
	global_load_dwordx4 v[130:133], v206, s[98:99] offset:128
	global_load_dwordx4 v[134:137], v207, s[98:99] offset:128
	global_load_dwordx4 v[138:141], v208, s[98:99] offset:128
	global_load_dwordx4 v[142:145], v238, s[98:99] offset:128
	global_load_dwordx4 v[146:149], v206, s[100:101] offset:128
	global_load_dwordx4 v[150:153], v207, s[100:101] offset:128
	global_load_dwordx4 v[154:157], v208, s[100:101] offset:128
	global_load_dwordx4 v[158:161], v238, s[100:101] offset:128
	s_add_u32 s98, s98, 0x100
	s_addc_u32 s99, s99, 0
	s_add_u32 s100, s100, 0x100
	s_addc_u32 s101, s101, 0
	v_and_b32_e32 v239, 31, v165
	v_bfe_u32 v0, v165, 5, 1
	v_lshrrev_b32_e32 v179, 8, v165
	v_lshl_or_b32 v178, v179, 7, v239
	v_mul_u32_u24_e32 v178, 0x90, v178
	v_lshl_add_u32 v178, v0, 4, v178
	v_bfe_u32 v179, v165, 6, 2
	v_lshl_or_b32 v179, v179, 6, v239
	v_mul_u32_u24_e32 v179, 0x90, v179
	v_lshl_add_u32 v179, v0, 4, v179
	s_mov_b32 s12, 0x12000
	s_mov_b32 s13, 13
	s_barrier
	s_waitcnt vmcnt(15)
	ds_write_b128 v180, v[2:5]
	s_waitcnt vmcnt(14)
	ds_write_b128 v180, v[6:9] offset:9216
	s_waitcnt vmcnt(13)
	ds_write_b128 v180, v[10:13] offset:18432
	s_waitcnt vmcnt(12)
	ds_write_b128 v180, v[14:17] offset:27648
	s_waitcnt vmcnt(11)
	ds_write_b128 v180, v[18:21] offset:36864
	s_waitcnt vmcnt(10)
	ds_write_b128 v180, v[22:25] offset:46080
	s_waitcnt vmcnt(9)
	ds_write_b128 v180, v[26:29] offset:55296
	s_waitcnt vmcnt(8)
	ds_write_b128 v180, v[30:33] offset:64512
	v_add_u32_e32 v180, 0x12000, v180
	s_waitcnt lgkmcnt(0)
	s_barrier
	ds_read_b128 v[194:197], v179 offset:36864
	ds_read_b128 v[166:169], v178
	ds_read_b128 v[198:201], v179 offset:41472
	ds_read_b128 v[170:173], v178 offset:4608
	ds_read_b128 v[174:177], v178 offset:9216
	ds_read_b128 v[190:193], v178 offset:13824
	s_waitcnt lgkmcnt(4)
	v_mfma_f32_32x32x16_bf16 v[114:129], v[166:169], v[194:197], 0
	ds_read_b128 v[234:237], v179 offset:36896
	s_waitcnt lgkmcnt(4)
	v_mfma_f32_32x32x16_bf16 v[98:113], v[166:169], v[198:201], 0
	ds_read_b128 v[218:221], v178 offset:32
	s_waitcnt vmcnt(7)
	ds_write_b128 v180, v[130:133]
	global_load_dwordx4 v[130:133], v206, s[98:99]
	s_waitcnt lgkmcnt(5)
	v_mfma_f32_32x32x16_bf16 v[82:97], v[170:173], v[194:197], 0
	ds_read_b128 v[202:205], v179 offset:41504
	v_mfma_f32_32x32x16_bf16 v[66:81], v[170:173], v[198:201], 0
	ds_read_b128 v[222:225], v178 offset:4640
	s_waitcnt vmcnt(7)
	ds_write_b128 v180, v[134:137] offset:9216
	global_load_dwordx4 v[134:137], v207, s[98:99]
	s_waitcnt lgkmcnt(7)
	v_mfma_f32_32x32x16_bf16 v[50:65], v[174:177], v[194:197], 0
	ds_read_b128 v[226:229], v178 offset:9248
	v_mfma_f32_32x32x16_bf16 v[34:49], v[174:177], v[198:201], 0
	ds_read_b128 v[230:233], v178 offset:13856
	s_waitcnt vmcnt(7)
	ds_write_b128 v180, v[138:141] offset:18432
	global_load_dwordx4 v[138:141], v208, s[98:99]
	s_waitcnt lgkmcnt(9)
	v_mfma_f32_32x32x16_bf16 v[18:33], v[190:193], v[194:197], 0
	v_mfma_f32_32x32x16_bf16 v[2:17], v[190:193], v[198:201], 0
	s_waitcnt vmcnt(7)
	ds_write_b128 v180, v[142:145] offset:27648
	global_load_dwordx4 v[142:145], v238, s[98:99]
	s_waitcnt lgkmcnt(8)
	v_mfma_f32_32x32x16_bf16 v[114:129], v[218:221], v[234:237], v[114:129]
	ds_read_b128 v[194:197], v179 offset:36928
	s_waitcnt lgkmcnt(7)
	v_mfma_f32_32x32x16_bf16 v[98:113], v[218:221], v[202:205], v[98:113]
	ds_read_b128 v[166:169], v178 offset:64
	s_waitcnt vmcnt(7)
	ds_write_b128 v180, v[146:149] offset:36864
	global_load_dwordx4 v[146:149], v206, s[100:101]
	s_waitcnt lgkmcnt(8)
	v_mfma_f32_32x32x16_bf16 v[82:97], v[222:225], v[234:237], v[82:97]
	ds_read_b128 v[198:201], v179 offset:41536
	v_mfma_f32_32x32x16_bf16 v[66:81], v[222:225], v[202:205], v[66:81]
	ds_read_b128 v[170:173], v178 offset:4672
	s_waitcnt vmcnt(7)
	ds_write_b128 v180, v[150:153] offset:46080
	global_load_dwordx4 v[150:153], v207, s[100:101]
	s_waitcnt lgkmcnt(9)
	v_mfma_f32_32x32x16_bf16 v[50:65], v[226:229], v[234:237], v[50:65]
	ds_read_b128 v[174:177], v178 offset:9280
	v_mfma_f32_32x32x16_bf16 v[34:49], v[226:229], v[202:205], v[34:49]
	ds_read_b128 v[190:193], v178 offset:13888
	s_waitcnt vmcnt(7)
	ds_write_b128 v180, v[154:157] offset:55296
	global_load_dwordx4 v[154:157], v208, s[100:101]
	s_waitcnt lgkmcnt(11)
	v_mfma_f32_32x32x16_bf16 v[18:33], v[230:233], v[234:237], v[18:33]
	v_mfma_f32_32x32x16_bf16 v[2:17], v[230:233], v[202:205], v[2:17]
	s_waitcnt vmcnt(7)
	ds_write_b128 v180, v[158:161] offset:64512
	global_load_dwordx4 v[158:161], v238, s[100:101]
	v_subrev_u32_e32 v180, s12, v180
	s_waitcnt lgkmcnt(8)
	v_mfma_f32_32x32x16_bf16 v[114:129], v[166:169], v[194:197], v[114:129]
	ds_read_b128 v[234:237], v179 offset:36960
	s_waitcnt lgkmcnt(7)
	v_mfma_f32_32x32x16_bf16 v[98:113], v[166:169], v[198:201], v[98:113]
	ds_read_b128 v[218:221], v178 offset:96
	s_waitcnt lgkmcnt(7)
	v_mfma_f32_32x32x16_bf16 v[82:97], v[170:173], v[194:197], v[82:97]
	ds_read_b128 v[202:205], v179 offset:41568
	v_mfma_f32_32x32x16_bf16 v[66:81], v[170:173], v[198:201], v[66:81]
	ds_read_b128 v[222:225], v178 offset:4704
	s_waitcnt lgkmcnt(7)
	v_mfma_f32_32x32x16_bf16 v[50:65], v[174:177], v[194:197], v[50:65]
	ds_read_b128 v[226:229], v178 offset:9312
	v_mfma_f32_32x32x16_bf16 v[34:49], v[174:177], v[198:201], v[34:49]
	ds_read_b128 v[230:233], v178 offset:13920
	v_add_u32_e32 v178, s12, v178
	v_add_u32_e32 v179, s12, v179
	s_waitcnt lgkmcnt(8)
	v_mfma_f32_32x32x16_bf16 v[18:33], v[190:193], v[194:197], v[18:33]
	v_mfma_f32_32x32x16_bf16 v[2:17], v[190:193], v[198:201], v[2:17]
	s_sub_u32 s12, 0, s12
	s_add_u32 s98, s98, 0x80
	s_addc_u32 s99, s99, 0
	s_add_u32 s100, s100, 0x80
	s_addc_u32 s101, s101, 0
	s_waitcnt lgkmcnt(0)
; #define G5_LOAD(k0)                                                                 \
;   {                                                                                 \
;     _Pragma("unroll") for (int i_ = 0; i_ < 4; ++i_) ra[i_] = ldg16(Ap + (size_t)(i_ * 64) * lda + (k0)); \
;     _Pragma("unroll") for (int i_ = 0; i_ < 4; ++i_) rb[i_] = ldg16(Bp + (size_t)(i_ * 64) * ldb + (k0)); \
;   }
; #define G5_STORE(s)                                                                 \
;   {                                                                                 \
;     _Pragma("unroll") for (int i_ = 0; i_ < 4; ++i_) *(u32x4*)(Sw + (s) * STG + i_ * 64 * GS) = ra[i_]; \
;     _Pragma("unroll") for (int i_ = 0; i_ < 4; ++i_) *(u32x4*)(Sw + (s) * STG + 256 * GS + i_ * 64 * GS) = rb[i_]; \
;   }
; template <typename Epi>
; DI void gemm_tile512(const u16* __restrict__ A, int lda, const u16* __restrict__ Bt, int ldb, int K, char* lds_all, Epi epi) {
;     ...
;   const int nk = K >> 6;
;   __syncthreads();
;   G5_LOAD(0);
;   G5_STORE(0);
;   G5_LOAD(64);
;   __syncthreads();
;   for (int kt = 0; kt + 2 < nk; ++kt) {
;     const int cur = kt & 1;
;     G5_COMPUTE(cur);
;     G5_STORE(cur ^ 1);
;     G5_LOAD((kt + 2) << 6);
;     __syncthreads();
;   }
.Lgemm_loop_m0_0:
	s_barrier
	ds_read_b128 v[194:197], v179 offset:36864
	ds_read_b128 v[166:169], v178
	v_mfma_f32_32x32x16_bf16 v[114:129], v[218:221], v[234:237], v[114:129]
	ds_read_b128 v[198:201], v179 offset:41472
	v_mfma_f32_32x32x16_bf16 v[98:113], v[218:221], v[202:205], v[98:113]
	ds_read_b128 v[170:173], v178 offset:4608
	v_mfma_f32_32x32x16_bf16 v[82:97], v[222:225], v[234:237], v[82:97]
	ds_read_b128 v[174:177], v178 offset:9216
	v_mfma_f32_32x32x16_bf16 v[66:81], v[222:225], v[202:205], v[66:81]
	ds_read_b128 v[190:193], v178 offset:13824
	v_mfma_f32_32x32x16_bf16 v[50:65], v[226:229], v[234:237], v[50:65]
	v_mfma_f32_32x32x16_bf16 v[34:49], v[226:229], v[202:205], v[34:49]
	v_mfma_f32_32x32x16_bf16 v[18:33], v[230:233], v[234:237], v[18:33]
	v_mfma_f32_32x32x16_bf16 v[2:17], v[230:233], v[202:205], v[2:17]
	s_waitcnt lgkmcnt(4)
	v_mfma_f32_32x32x16_bf16 v[114:129], v[166:169], v[194:197], v[114:129]
	ds_read_b128 v[234:237], v179 offset:36896
	s_waitcnt lgkmcnt(4)
	v_mfma_f32_32x32x16_bf16 v[98:113], v[166:169], v[198:201], v[98:113]
	ds_read_b128 v[218:221], v178 offset:32
	s_waitcnt vmcnt(7)
	ds_write_b128 v180, v[130:133]
	global_load_dwordx4 v[130:133], v206, s[98:99]
	s_waitcnt lgkmcnt(5)
	v_mfma_f32_32x32x16_bf16 v[82:97], v[170:173], v[194:197], v[82:97]
	ds_read_b128 v[202:205], v179 offset:41504
	v_mfma_f32_32x32x16_bf16 v[66:81], v[170:173], v[198:201], v[66:81]
	ds_read_b128 v[222:225], v178 offset:4640
	s_waitcnt vmcnt(7)
	ds_write_b128 v180, v[134:137] offset:9216
	global_load_dwordx4 v[134:137], v207, s[98:99]
	s_waitcnt lgkmcnt(7)
	v_mfma_f32_32x32x16_bf16 v[50:65], v[174:177], v[194:197], v[50:65]
	ds_read_b128 v[226:229], v178 offset:9248
	v_mfma_f32_32x32x16_bf16 v[34:49], v[174:177], v[198:201], v[34:49]
	ds_read_b128 v[230:233], v178 offset:13856
	s_waitcnt vmcnt(7)
	ds_write_b128 v180, v[138:141] offset:18432
	global_load_dwordx4 v[138:141], v208, s[98:99]
	s_waitcnt lgkmcnt(9)
	v_mfma_f32_32x32x16_bf16 v[18:33], v[190:193], v[194:197], v[18:33]
	v_mfma_f32_32x32x16_bf16 v[2:17], v[190:193], v[198:201], v[2:17]
	s_waitcnt vmcnt(7)
	ds_write_b128 v180, v[142:145] offset:27648
	global_load_dwordx4 v[142:145], v238, s[98:99]
	s_waitcnt lgkmcnt(8)
	v_mfma_f32_32x32x16_bf16 v[114:129], v[218:221], v[234:237], v[114:129]
	ds_read_b128 v[194:197], v179 offset:36928
	s_waitcnt lgkmcnt(7)
	v_mfma_f32_32x32x16_bf16 v[98:113], v[218:221], v[202:205], v[98:113]
	ds_read_b128 v[166:169], v178 offset:64
	s_waitcnt vmcnt(7)
	ds_write_b128 v180, v[146:149] offset:36864
	global_load_dwordx4 v[146:149], v206, s[100:101]
	s_waitcnt lgkmcnt(8)
	v_mfma_f32_32x32x16_bf16 v[82:97], v[222:225], v[234:237], v[82:97]
	ds_read_b128 v[198:201], v179 offset:41536
	v_mfma_f32_32x32x16_bf16 v[66:81], v[222:225], v[202:205], v[66:81]
	ds_read_b128 v[170:173], v178 offset:4672
	s_waitcnt vmcnt(7)
	ds_write_b128 v180, v[150:153] offset:46080
	global_load_dwordx4 v[150:153], v207, s[100:101]
	s_waitcnt lgkmcnt(9)
	v_mfma_f32_32x32x16_bf16 v[50:65], v[226:229], v[234:237], v[50:65]
	ds_read_b128 v[174:177], v178 offset:9280
	v_mfma_f32_32x32x16_bf16 v[34:49], v[226:229], v[202:205], v[34:49]
	ds_read_b128 v[190:193], v178 offset:13888
	s_waitcnt vmcnt(7)
	ds_write_b128 v180, v[154:157] offset:55296
	global_load_dwordx4 v[154:157], v208, s[100:101]
	s_waitcnt lgkmcnt(11)
	v_mfma_f32_32x32x16_bf16 v[18:33], v[230:233], v[234:237], v[18:33]
	v_mfma_f32_32x32x16_bf16 v[2:17], v[230:233], v[202:205], v[2:17]
	s_waitcnt vmcnt(7)
	ds_write_b128 v180, v[158:161] offset:64512
	global_load_dwordx4 v[158:161], v238, s[100:101]
	v_subrev_u32_e32 v180, s12, v180
	s_waitcnt lgkmcnt(8)
	v_mfma_f32_32x32x16_bf16 v[114:129], v[166:169], v[194:197], v[114:129]
	ds_read_b128 v[234:237], v179 offset:36960
	s_waitcnt lgkmcnt(7)
	v_mfma_f32_32x32x16_bf16 v[98:113], v[166:169], v[198:201], v[98:113]
	ds_read_b128 v[218:221], v178 offset:96
	s_waitcnt lgkmcnt(7)
	v_mfma_f32_32x32x16_bf16 v[82:97], v[170:173], v[194:197], v[82:97]
	ds_read_b128 v[202:205], v179 offset:41568
	v_mfma_f32_32x32x16_bf16 v[66:81], v[170:173], v[198:201], v[66:81]
	ds_read_b128 v[222:225], v178 offset:4704
	s_waitcnt lgkmcnt(7)
	v_mfma_f32_32x32x16_bf16 v[50:65], v[174:177], v[194:197], v[50:65]
	ds_read_b128 v[226:229], v178 offset:9312
	v_mfma_f32_32x32x16_bf16 v[34:49], v[174:177], v[198:201], v[34:49]
	ds_read_b128 v[230:233], v178 offset:13920
	v_add_u32_e32 v178, s12, v178
	v_add_u32_e32 v179, s12, v179
	s_waitcnt lgkmcnt(8)
	v_mfma_f32_32x32x16_bf16 v[18:33], v[190:193], v[194:197], v[18:33]
	v_mfma_f32_32x32x16_bf16 v[2:17], v[190:193], v[198:201], v[2:17]
	s_sub_u32 s12, 0, s12
	s_add_u32 s98, s98, 0x80
	s_addc_u32 s99, s99, 0
	s_add_u32 s100, s100, 0x80
	s_addc_u32 s101, s101, 0
	s_waitcnt lgkmcnt(0)
	s_sub_u32 s13, s13, 1
	s_cmp_lg_u32 s13, 0
	s_cbranch_scc1 .Lgemm_loop_m0_0
	s_barrier
; #define G5_STORE(s)                                                                 \
;   {                                                                                 \
;     _Pragma("unroll") for (int i_ = 0; i_ < 4; ++i_) *(u32x4*)(Sw + (s) * STG + i_ * 64 * GS) = ra[i_]; \
;     _Pragma("unroll") for (int i_ = 0; i_ < 4; ++i_) *(u32x4*)(Sw + (s) * STG + 256 * GS + i_ * 64 * GS) = rb[i_]; \
;   }
; template <typename Epi>
; DI void gemm_tile512(const u16* __restrict__ A, int lda, const u16* __restrict__ Bt, int ldb, int K, char* lds_all, Epi epi) {
;     ...
;   {
;     const int cur = (nk - 2) & 1;
;     G5_COMPUTE(cur);
;     G5_STORE(cur ^ 1);
;     __syncthreads();
	ds_read_b128 v[194:197], v179 offset:36864
	ds_read_b128 v[166:169], v178
	v_mfma_f32_32x32x16_bf16 v[114:129], v[218:221], v[234:237], v[114:129]
	ds_read_b128 v[198:201], v179 offset:41472
	v_mfma_f32_32x32x16_bf16 v[98:113], v[218:221], v[202:205], v[98:113]
	ds_read_b128 v[170:173], v178 offset:4608
	v_mfma_f32_32x32x16_bf16 v[82:97], v[222:225], v[234:237], v[82:97]
	ds_read_b128 v[174:177], v178 offset:9216
	v_mfma_f32_32x32x16_bf16 v[66:81], v[222:225], v[202:205], v[66:81]
	ds_read_b128 v[190:193], v178 offset:13824
	v_mfma_f32_32x32x16_bf16 v[50:65], v[226:229], v[234:237], v[50:65]
	v_mfma_f32_32x32x16_bf16 v[34:49], v[226:229], v[202:205], v[34:49]
	v_mfma_f32_32x32x16_bf16 v[18:33], v[230:233], v[234:237], v[18:33]
	v_mfma_f32_32x32x16_bf16 v[2:17], v[230:233], v[202:205], v[2:17]
	s_waitcnt lgkmcnt(4)
	v_mfma_f32_32x32x16_bf16 v[114:129], v[166:169], v[194:197], v[114:129]
	ds_read_b128 v[234:237], v179 offset:36896
	s_waitcnt lgkmcnt(4)
	v_mfma_f32_32x32x16_bf16 v[98:113], v[166:169], v[198:201], v[98:113]
	ds_read_b128 v[218:221], v178 offset:32
	s_waitcnt vmcnt(7)
	ds_write_b128 v180, v[130:133]
	s_waitcnt lgkmcnt(5)
	v_mfma_f32_32x32x16_bf16 v[82:97], v[170:173], v[194:197], v[82:97]
	ds_read_b128 v[202:205], v179 offset:41504
	v_mfma_f32_32x32x16_bf16 v[66:81], v[170:173], v[198:201], v[66:81]
	ds_read_b128 v[222:225], v178 offset:4640
	s_waitcnt vmcnt(6)
	ds_write_b128 v180, v[134:137] offset:9216
	s_waitcnt lgkmcnt(7)
	v_mfma_f32_32x32x16_bf16 v[50:65], v[174:177], v[194:197], v[50:65]
	ds_read_b128 v[226:229], v178 offset:9248
	v_mfma_f32_32x32x16_bf16 v[34:49], v[174:177], v[198:201], v[34:49]
	ds_read_b128 v[230:233], v178 offset:13856
	s_waitcnt vmcnt(5)
	ds_write_b128 v180, v[138:141] offset:18432
	s_waitcnt lgkmcnt(9)
	v_mfma_f32_32x32x16_bf16 v[18:33], v[190:193], v[194:197], v[18:33]
	v_mfma_f32_32x32x16_bf16 v[2:17], v[190:193], v[198:201], v[2:17]
	s_waitcnt vmcnt(4)
	ds_write_b128 v180, v[142:145] offset:27648
	s_waitcnt lgkmcnt(8)
	v_mfma_f32_32x32x16_bf16 v[114:129], v[218:221], v[234:237], v[114:129]
	ds_read_b128 v[194:197], v179 offset:36928
	s_waitcnt lgkmcnt(7)
	v_mfma_f32_32x32x16_bf16 v[98:113], v[218:221], v[202:205], v[98:113]
	ds_read_b128 v[166:169], v178 offset:64
	s_waitcnt vmcnt(3)
	ds_write_b128 v180, v[146:149] offset:36864
	s_waitcnt lgkmcnt(8)
	v_mfma_f32_32x32x16_bf16 v[82:97], v[222:225], v[234:237], v[82:97]
	ds_read_b128 v[198:201], v179 offset:41536
	v_mfma_f32_32x32x16_bf16 v[66:81], v[222:225], v[202:205], v[66:81]
	ds_read_b128 v[170:173], v178 offset:4672
	s_waitcnt vmcnt(2)
	ds_write_b128 v180, v[150:153] offset:46080
	s_waitcnt lgkmcnt(9)
	v_mfma_f32_32x32x16_bf16 v[50:65], v[226:229], v[234:237], v[50:65]
	ds_read_b128 v[174:177], v178 offset:9280
	v_mfma_f32_32x32x16_bf16 v[34:49], v[226:229], v[202:205], v[34:49]
	ds_read_b128 v[190:193], v178 offset:13888
	s_waitcnt vmcnt(1)
	ds_write_b128 v180, v[154:157] offset:55296
	s_waitcnt lgkmcnt(11)
	v_mfma_f32_32x32x16_bf16 v[18:33], v[230:233], v[234:237], v[18:33]
	v_mfma_f32_32x32x16_bf16 v[2:17], v[230:233], v[202:205], v[2:17]
	s_waitcnt vmcnt(0)
	ds_write_b128 v180, v[158:161] offset:64512
	v_subrev_u32_e32 v180, s12, v180
	s_waitcnt lgkmcnt(8)
	v_mfma_f32_32x32x16_bf16 v[114:129], v[166:169], v[194:197], v[114:129]
	ds_read_b128 v[234:237], v179 offset:36960
	s_waitcnt lgkmcnt(7)
	v_mfma_f32_32x32x16_bf16 v[98:113], v[166:169], v[198:201], v[98:113]
	ds_read_b128 v[218:221], v178 offset:96
	s_waitcnt lgkmcnt(7)
	v_mfma_f32_32x32x16_bf16 v[82:97], v[170:173], v[194:197], v[82:97]
	ds_read_b128 v[202:205], v179 offset:41568
	v_mfma_f32_32x32x16_bf16 v[66:81], v[170:173], v[198:201], v[66:81]
	ds_read_b128 v[222:225], v178 offset:4704
	s_waitcnt lgkmcnt(7)
	v_mfma_f32_32x32x16_bf16 v[50:65], v[174:177], v[194:197], v[50:65]
	ds_read_b128 v[226:229], v178 offset:9312
	v_mfma_f32_32x32x16_bf16 v[34:49], v[174:177], v[198:201], v[34:49]
	ds_read_b128 v[230:233], v178 offset:13920
	v_add_u32_e32 v178, s12, v178
	v_add_u32_e32 v179, s12, v179
	s_waitcnt lgkmcnt(8)
	v_mfma_f32_32x32x16_bf16 v[18:33], v[190:193], v[194:197], v[18:33]
	v_mfma_f32_32x32x16_bf16 v[2:17], v[190:193], v[198:201], v[2:17]
	s_sub_u32 s12, 0, s12
	s_waitcnt lgkmcnt(0)
	s_barrier
; template <typename Epi>
; DI void gemm_tile512(const u16* __restrict__ A, int lda, const u16* __restrict__ Bt, int ldb, int K, char* lds_all, Epi epi) {
;     ...
;     G5_COMPUTE(cur ^ 1);
	ds_read_b128 v[194:197], v179 offset:36864
	ds_read_b128 v[166:169], v178
	v_mfma_f32_32x32x16_bf16 v[114:129], v[218:221], v[234:237], v[114:129]
	ds_read_b128 v[198:201], v179 offset:41472
	v_mfma_f32_32x32x16_bf16 v[98:113], v[218:221], v[202:205], v[98:113]
	ds_read_b128 v[170:173], v178 offset:4608
	v_mfma_f32_32x32x16_bf16 v[82:97], v[222:225], v[234:237], v[82:97]
	ds_read_b128 v[174:177], v178 offset:9216
	v_mfma_f32_32x32x16_bf16 v[66:81], v[222:225], v[202:205], v[66:81]
	ds_read_b128 v[190:193], v178 offset:13824
	v_mfma_f32_32x32x16_bf16 v[50:65], v[226:229], v[234:237], v[50:65]
	v_mfma_f32_32x32x16_bf16 v[34:49], v[226:229], v[202:205], v[34:49]
	v_mfma_f32_32x32x16_bf16 v[18:33], v[230:233], v[234:237], v[18:33]
	v_mfma_f32_32x32x16_bf16 v[2:17], v[230:233], v[202:205], v[2:17]
	s_waitcnt lgkmcnt(4)
	v_mfma_f32_32x32x16_bf16 v[114:129], v[166:169], v[194:197], v[114:129]
	ds_read_b128 v[234:237], v179 offset:36896
	s_waitcnt lgkmcnt(4)
	v_mfma_f32_32x32x16_bf16 v[98:113], v[166:169], v[198:201], v[98:113]
	ds_read_b128 v[218:221], v178 offset:32
	s_waitcnt lgkmcnt(4)
	v_mfma_f32_32x32x16_bf16 v[82:97], v[170:173], v[194:197], v[82:97]
	ds_read_b128 v[202:205], v179 offset:41504
	v_mfma_f32_32x32x16_bf16 v[66:81], v[170:173], v[198:201], v[66:81]
	ds_read_b128 v[222:225], v178 offset:4640
	s_waitcnt lgkmcnt(5)
	v_mfma_f32_32x32x16_bf16 v[50:65], v[174:177], v[194:197], v[50:65]
	ds_read_b128 v[226:229], v178 offset:9248
	v_mfma_f32_32x32x16_bf16 v[34:49], v[174:177], v[198:201], v[34:49]
	ds_read_b128 v[230:233], v178 offset:13856
	s_waitcnt lgkmcnt(6)
	v_mfma_f32_32x32x16_bf16 v[18:33], v[190:193], v[194:197], v[18:33]
	v_mfma_f32_32x32x16_bf16 v[2:17], v[190:193], v[198:201], v[2:17]
	s_waitcnt lgkmcnt(4)
	v_mfma_f32_32x32x16_bf16 v[114:129], v[218:221], v[234:237], v[114:129]
	ds_read_b128 v[194:197], v179 offset:36928
	s_waitcnt lgkmcnt(4)
	v_mfma_f32_32x32x16_bf16 v[98:113], v[218:221], v[202:205], v[98:113]
	ds_read_b128 v[166:169], v178 offset:64
	s_waitcnt lgkmcnt(4)
	v_mfma_f32_32x32x16_bf16 v[82:97], v[222:225], v[234:237], v[82:97]
	ds_read_b128 v[198:201], v179 offset:41536
	v_mfma_f32_32x32x16_bf16 v[66:81], v[222:225], v[202:205], v[66:81]
	ds_read_b128 v[170:173], v178 offset:4672
	s_waitcnt lgkmcnt(5)
	v_mfma_f32_32x32x16_bf16 v[50:65], v[226:229], v[234:237], v[50:65]
	ds_read_b128 v[174:177], v178 offset:9280
	v_mfma_f32_32x32x16_bf16 v[34:49], v[226:229], v[202:205], v[34:49]
	ds_read_b128 v[190:193], v178 offset:13888
	s_waitcnt lgkmcnt(6)
	v_mfma_f32_32x32x16_bf16 v[18:33], v[230:233], v[234:237], v[18:33]
	v_mfma_f32_32x32x16_bf16 v[2:17], v[230:233], v[202:205], v[2:17]
	s_waitcnt lgkmcnt(4)
	v_mfma_f32_32x32x16_bf16 v[114:129], v[166:169], v[194:197], v[114:129]
	ds_read_b128 v[234:237], v179 offset:36960
	s_waitcnt lgkmcnt(4)
	v_mfma_f32_32x32x16_bf16 v[98:113], v[166:169], v[198:201], v[98:113]
	ds_read_b128 v[218:221], v178 offset:96
	s_waitcnt lgkmcnt(4)
	v_mfma_f32_32x32x16_bf16 v[82:97], v[170:173], v[194:197], v[82:97]
	ds_read_b128 v[202:205], v179 offset:41568
	v_mfma_f32_32x32x16_bf16 v[66:81], v[170:173], v[198:201], v[66:81]
	ds_read_b128 v[222:225], v178 offset:4704
	s_waitcnt lgkmcnt(5)
	v_mfma_f32_32x32x16_bf16 v[50:65], v[174:177], v[194:197], v[50:65]
	ds_read_b128 v[226:229], v178 offset:9312
	v_mfma_f32_32x32x16_bf16 v[34:49], v[174:177], v[198:201], v[34:49]
	ds_read_b128 v[230:233], v178 offset:13920
	s_waitcnt lgkmcnt(6)
	v_mfma_f32_32x32x16_bf16 v[18:33], v[190:193], v[194:197], v[18:33]
	v_mfma_f32_32x32x16_bf16 v[2:17], v[190:193], v[198:201], v[2:17]
	s_waitcnt lgkmcnt(0)
; DI int crow(int reg, int h) { return (reg & 3) + 8 * (reg >> 2) + 4 * h; }
; template <typename Epi>
; DI void gemm_tile512(const u16* __restrict__ A, int lda, const u16* __restrict__ Bt, int ldb, int K, char* lds_all, Epi epi) {
;     ...
; #pragma unroll 1
;   for (int half = 0; half < 2; ++half) {
;     __syncthreads();
;     if (wm == half) {
; #pragma unroll
;       for (int i = 0; i < 4; ++i)
; #pragma unroll
;         for (int j = 0; j < 2; ++j)
; #pragma unroll
;           for (int g = 0; g < 16; ++g) Cs[(i * 32 + crow(g, h)) * CSW + wn * 64 + j * 32 + r] = acc[i][j][g];
	v_mfma_f32_32x32x16_bf16 v[114:129], v[218:221], v[234:237], v[114:129]
	v_mfma_f32_32x32x16_bf16 v[98:113], v[218:221], v[202:205], v[98:113]
	v_mfma_f32_32x32x16_bf16 v[82:97], v[222:225], v[234:237], v[82:97]
	v_mfma_f32_32x32x16_bf16 v[66:81], v[222:225], v[202:205], v[66:81]
	v_mfma_f32_32x32x16_bf16 v[50:65], v[226:229], v[234:237], v[50:65]
	v_mfma_f32_32x32x16_bf16 v[34:49], v[226:229], v[202:205], v[34:49]
	v_mfma_f32_32x32x16_bf16 v[18:33], v[230:233], v[234:237], v[18:33]
	v_mfma_f32_32x32x16_bf16 v[2:17], v[230:233], v[202:205], v[2:17]
	v_mov_b32_e32 v190, 0x10c20
	v_mov_b32_e32 v191, 0x11040
	v_mov_b32_e32 v192, 0x11460
	v_mov_b32_e32 v193, 0x12900
	v_mov_b32_e32 v194, 0x12d20
	v_mov_b32_e32 v195, 0x13140
	v_mov_b32_e32 v196, 0x13560
	v_mov_b32_e32 v197, 0x14a00
	v_mov_b32_e32 v198, 0x14e20
	v_mov_b32_e32 v199, 0x15240
	v_mov_b32_e32 v200, 0x15660
	v_mov_b32_e32 v201, 0x16b00
	v_mov_b32_e32 v202, 0x16f20
	v_mov_b32_e32 v203, 0x17340
	v_mov_b32_e32 v204, 0x17760
	v_mov_b32_e32 v205, 0x18c00
	v_mov_b32_e32 v206, 0x19020
	v_mov_b32_e32 v207, 0x19440
	v_mov_b32_e32 v208, 0x10800
	v_lshrrev_b32_e32 v218, 8, v165
	v_bfe_u32 v219, v165, 5, 1
	v_and_b32_e32 v220, 31, v165
	v_bfe_u32 v221, v165, 6, 2
	s_cmpk_eq_i32 s18, 0x600
	s_mov_b32 s10, 0
	s_mov_b64 s[6:7], -1
	v_mov_b32_e32 v244, 0x1b960
	v_mov_b32_e32 v245, 0x1ce00
	v_mov_b32_e32 v246, 0x1d220
	v_mov_b32_e32 v247, 0x1d640
	v_mov_b32_e32 v240, 0x19860
	v_mov_b32_e32 v241, 0x1ad00
	v_mov_b32_e32 v242, 0x1b120
	v_mov_b32_e32 v243, 0x1b540
	s_movk_i32 s4, 0x1080
	v_mad_u32_u24 v167, v219, s4, v243
	v_mad_u32_u24 v168, v219, s4, v244
	v_mad_u32_u24 v169, v219, s4, v245
	v_mad_u32_u24 v170, v219, s4, v246
	v_mad_u32_u24 v171, v219, s4, v247
	v_mad_u32_u24 v154, v219, s4, v202
	v_mad_u32_u24 v155, v219, s4, v203
	v_mad_u32_u24 v156, v219, s4, v204
	v_mad_u32_u24 v157, v219, s4, v205
	v_mad_u32_u24 v158, v219, s4, v206
	v_mad_u32_u24 v159, v219, s4, v207
	v_mad_u32_u24 v160, v219, s4, v240
	v_mad_u32_u24 v161, v219, s4, v241
	v_lshlrev_b32_e32 v0, 8, v221
	v_lshl_or_b32 v0, v220, 2, v0
	v_mad_u32_u24 v166, v219, s4, v242
	v_add_u32_e32 v154, v0, v154
	v_add_u32_e32 v155, v0, v155
	v_add_u32_e32 v156, v0, v156
	v_add_u32_e32 v157, v0, v157
	v_add_u32_e32 v158, v0, v158
	v_add_u32_e32 v159, v0, v159
	v_mad_u32_u24 v130, v219, s4, v208
	v_mad_u32_u24 v131, v219, s4, v190
	v_mad_u32_u24 v132, v219, s4, v191
	v_mad_u32_u24 v133, v219, s4, v192
	v_add_u32_e32 v160, v0, v160
	v_add_u32_e32 v161, v0, v161
	v_add_u32_e32 v166, v0, v166
	v_add_u32_e32 v167, v0, v167
	v_add_u32_e32 v168, v0, v168
	v_add_u32_e32 v169, v0, v169
	v_add_u32_e32 v170, v0, v170
	v_add_u32_e32 v171, v0, v171
	v_mad_u32_u24 v134, v219, s4, v193
	v_mad_u32_u24 v135, v219, s4, v194
	v_mad_u32_u24 v136, v219, s4, v195
	v_mad_u32_u24 v137, v219, s4, v196
	v_mov_b32_e32 v141, 0x1da60
	v_mad_u32_u24 v172, v219, s4, v141
	v_mov_b32_e32 v141, 0x1ef00
	v_mad_u32_u24 v173, v219, s4, v141
	v_mov_b32_e32 v141, 0x1f320
	v_mad_u32_u24 v174, v219, s4, v141
	v_mov_b32_e32 v141, 0x1f740
	v_mad_u32_u24 v175, v219, s4, v141
	v_mov_b32_e32 v141, 0x1fb60
	v_mad_u32_u24 v138, v219, s4, v197
	v_mad_u32_u24 v139, v219, s4, v198
	v_mad_u32_u24 v176, v219, s4, v141
	v_mad_u32_u24 v140, v219, s4, v0
	v_add_u32_e32 v141, v0, v130
	v_mad_u32_u24 v151, v219, s4, v199
	v_mad_u32_u24 v152, v219, s4, v200
	v_mad_u32_u24 v153, v219, s4, v201
	s_cselect_b64 s[4:5], -1, 0
	v_add_u32_e32 v142, v0, v131
	v_add_u32_e32 v143, v0, v132
	v_add_u32_e32 v144, v0, v133
	v_add_u32_e32 v145, v0, v134
	v_add_u32_e32 v146, v0, v135
	v_add_u32_e32 v147, v0, v136
	v_add_u32_e32 v148, v0, v137
	v_add_u32_e32 v149, v0, v138
	v_add_u32_e32 v150, v0, v139
	v_add_u32_e32 v151, v0, v151
	v_add_u32_e32 v152, v0, v152
	v_add_u32_e32 v153, v0, v153
	v_add_u32_e32 v219, v0, v172
	v_add_u32_e32 v220, v0, v173
	v_add_u32_e32 v221, v0, v174
	v_add_u32_e32 v222, v0, v175
	v_add_u32_e32 v223, v0, v176
	s_branch .LBB0_202

; #define G5_LOAD(k0)                                                                 \
;   {                                                                                 \
;     _Pragma("unroll") for (int i_ = 0; i_ < 4; ++i_) ra[i_] = ldg16(Ap + (size_t)(i_ * 64) * lda + (k0)); \
;     _Pragma("unroll") for (int i_ = 0; i_ < 4; ++i_) rb[i_] = ldg16(Bp + (size_t)(i_ * 64) * ldb + (k0)); \
;   }
; #define G5_STORE(s)                                                                 \
;   {                                                                                 \
;     _Pragma("unroll") for (int i_ = 0; i_ < 4; ++i_) *(u32x4*)(Sw + (s) * STG + i_ * 64 * GS) = ra[i_]; \
;     _Pragma("unroll") for (int i_ = 0; i_ < 4; ++i_) *(u32x4*)(Sw + (s) * STG + 256 * GS + i_ * 64 * GS) = rb[i_]; \
;   }
; template <typename Epi>
; DI void gemm_tile512(const u16* __restrict__ A, int lda, const u16* __restrict__ Bt, int ldb, int K, char* lds_all, Epi epi) {
;     ...
;   const int lrow = tid >> 3, lcol = (tid & 7) * 8;
;   const u16* Ap = A + (size_t)lrow * lda + lcol;
;   const u16* Bp = Bt + (size_t)lrow * ldb + lcol;
;   u16* Sw = S0 + lrow * GS + lcol;
;   u32x4 ra[4], rb[4];
;     ...
;   const int nk = K >> 6;
;   __syncthreads();
;   G5_LOAD(0);
;   G5_STORE(0);
;   G5_LOAD(64);
;   __syncthreads();
;   for (int kt = 0; kt + 2 < nk; ++kt) {
;     const int cur = kt & 1;
;     G5_COMPUTE(cur);
;     G5_STORE(cur ^ 1);
;     G5_LOAD((kt + 2) << 6);
;     __syncthreads();
;   }
.LBB0_789:
	s_lshl_b32 s17, s13, 9
	s_lshl_b32 s13, s26, 8
	s_and_b32 s13, s13, 0x100
	s_lshl_b32 s29, s12, 10
	s_lshl_b32 s12, s26, 7
	s_or_b32 s27, s13, s17
	s_sub_i32 s12, s12, s29
	s_and_b32 s28, s12, 0xffffff00
	s_mul_i32 s12, s27, 0x900
	v_readlane_b32 s14, v250, 46
	s_mul_hi_i32 s13, s27, 0x900
	s_add_u32 s12, s14, s12
	v_readlane_b32 s14, v250, 47
	s_addc_u32 s13, s14, s13
	s_mul_i32 s14, s28, 0x900
	s_mul_hi_i32 s15, s28, 0x900
	s_add_u32 s14, s38, s14
	s_addc_u32 s15, s39, s15
	s_mov_b64 s[98:99], s[12:13]
	s_mov_b64 s[100:101], s[14:15]
	v_lshrrev_b32_e32 v239, 3, v165
	v_and_b32_e32 v0, 7, v165
	v_mul_u32_u24_e32 v206, 0x900, v239
	v_lshl_add_u32 v206, v0, 4, v206
	v_add_u32_e32 v207, 0x24000, v206
	v_add_u32_e32 v208, 0x48000, v206
	v_add_u32_e32 v238, 0x6c000, v206
	v_mul_u32_u24_e32 v180, 0x90, v239
	v_lshl_add_u32 v180, v0, 4, v180
	global_load_dwordx4 v[2:5], v206, s[98:99]
	global_load_dwordx4 v[6:9], v207, s[98:99]
	global_load_dwordx4 v[10:13], v208, s[98:99]
	global_load_dwordx4 v[14:17], v238, s[98:99]
	global_load_dwordx4 v[18:21], v206, s[100:101]
	global_load_dwordx4 v[22:25], v207, s[100:101]
	global_load_dwordx4 v[26:29], v208, s[100:101]
	global_load_dwordx4 v[30:33], v238, s[100:101]
	global_load_dwordx4 v[130:133], v206, s[98:99] offset:128
	global_load_dwordx4 v[134:137], v207, s[98:99] offset:128
	global_load_dwordx4 v[138:141], v208, s[98:99] offset:128
	global_load_dwordx4 v[142:145], v238, s[98:99] offset:128
	global_load_dwordx4 v[146:149], v206, s[100:101] offset:128
	global_load_dwordx4 v[150:153], v207, s[100:101] offset:128
	global_load_dwordx4 v[154:157], v208, s[100:101] offset:128
	global_load_dwordx4 v[158:161], v238, s[100:101] offset:128
	s_add_u32 s98, s98, 0x100
	s_addc_u32 s99, s99, 0
	s_add_u32 s100, s100, 0x100
	s_addc_u32 s101, s101, 0
	v_and_b32_e32 v239, 31, v165
	v_bfe_u32 v0, v165, 5, 1
	v_lshrrev_b32_e32 v179, 8, v165
	v_lshl_or_b32 v178, v179, 7, v239
	v_mul_u32_u24_e32 v178, 0x90, v178
	v_lshl_add_u32 v178, v0, 4, v178
	v_bfe_u32 v179, v165, 6, 2
	v_lshl_or_b32 v179, v179, 6, v239
	v_mul_u32_u24_e32 v179, 0x90, v179
	v_lshl_add_u32 v179, v0, 4, v179
	s_mov_b32 s20, 0x12000
	s_mov_b32 s21, 13
	s_barrier
	s_waitcnt vmcnt(15)
	ds_write_b128 v180, v[2:5]
	s_waitcnt vmcnt(14)
	ds_write_b128 v180, v[6:9] offset:9216
	s_waitcnt vmcnt(13)
	ds_write_b128 v180, v[10:13] offset:18432
	s_waitcnt vmcnt(12)
	ds_write_b128 v180, v[14:17] offset:27648
	s_waitcnt vmcnt(11)
	ds_write_b128 v180, v[18:21] offset:36864
	s_waitcnt vmcnt(10)
	ds_write_b128 v180, v[22:25] offset:46080
	s_waitcnt vmcnt(9)
	ds_write_b128 v180, v[26:29] offset:55296
	s_waitcnt vmcnt(8)
	ds_write_b128 v180, v[30:33] offset:64512
	v_add_u32_e32 v180, 0x12000, v180
	s_waitcnt lgkmcnt(0)
	s_barrier
	ds_read_b128 v[194:197], v179 offset:36864
	ds_read_b128 v[166:169], v178
	ds_read_b128 v[198:201], v179 offset:41472
	ds_read_b128 v[170:173], v178 offset:4608
	ds_read_b128 v[174:177], v178 offset:9216
	ds_read_b128 v[190:193], v178 offset:13824
	s_waitcnt lgkmcnt(4)
	v_mfma_f32_32x32x16_bf16 v[114:129], v[166:169], v[194:197], 0
	ds_read_b128 v[234:237], v179 offset:36896
	s_waitcnt lgkmcnt(4)
	v_mfma_f32_32x32x16_bf16 v[98:113], v[166:169], v[198:201], 0
	ds_read_b128 v[218:221], v178 offset:32
	s_waitcnt vmcnt(7)
	ds_write_b128 v180, v[130:133]
	global_load_dwordx4 v[130:133], v206, s[98:99]
	s_waitcnt lgkmcnt(5)
	v_mfma_f32_32x32x16_bf16 v[82:97], v[170:173], v[194:197], 0
	ds_read_b128 v[202:205], v179 offset:41504
	v_mfma_f32_32x32x16_bf16 v[66:81], v[170:173], v[198:201], 0
	ds_read_b128 v[222:225], v178 offset:4640
	s_waitcnt vmcnt(7)
	ds_write_b128 v180, v[134:137] offset:9216
	global_load_dwordx4 v[134:137], v207, s[98:99]
	s_waitcnt lgkmcnt(7)
	v_mfma_f32_32x32x16_bf16 v[50:65], v[174:177], v[194:197], 0
	ds_read_b128 v[226:229], v178 offset:9248
	v_mfma_f32_32x32x16_bf16 v[34:49], v[174:177], v[198:201], 0
	ds_read_b128 v[230:233], v178 offset:13856
	s_waitcnt vmcnt(7)
	ds_write_b128 v180, v[138:141] offset:18432
	global_load_dwordx4 v[138:141], v208, s[98:99]
	s_waitcnt lgkmcnt(9)
	v_mfma_f32_32x32x16_bf16 v[18:33], v[190:193], v[194:197], 0
	v_mfma_f32_32x32x16_bf16 v[2:17], v[190:193], v[198:201], 0
	s_waitcnt vmcnt(7)
	ds_write_b128 v180, v[142:145] offset:27648
	global_load_dwordx4 v[142:145], v238, s[98:99]
	s_waitcnt lgkmcnt(8)
	v_mfma_f32_32x32x16_bf16 v[114:129], v[218:221], v[234:237], v[114:129]
	ds_read_b128 v[194:197], v179 offset:36928
	s_waitcnt lgkmcnt(7)
	v_mfma_f32_32x32x16_bf16 v[98:113], v[218:221], v[202:205], v[98:113]
	ds_read_b128 v[166:169], v178 offset:64
	s_waitcnt vmcnt(7)
	ds_write_b128 v180, v[146:149] offset:36864
	global_load_dwordx4 v[146:149], v206, s[100:101]
	s_waitcnt lgkmcnt(8)
	v_mfma_f32_32x32x16_bf16 v[82:97], v[222:225], v[234:237], v[82:97]
	ds_read_b128 v[198:201], v179 offset:41536
	v_mfma_f32_32x32x16_bf16 v[66:81], v[222:225], v[202:205], v[66:81]
	ds_read_b128 v[170:173], v178 offset:4672
	s_waitcnt vmcnt(7)
	ds_write_b128 v180, v[150:153] offset:46080
	global_load_dwordx4 v[150:153], v207, s[100:101]
	s_waitcnt lgkmcnt(9)
	v_mfma_f32_32x32x16_bf16 v[50:65], v[226:229], v[234:237], v[50:65]
	ds_read_b128 v[174:177], v178 offset:9280
	v_mfma_f32_32x32x16_bf16 v[34:49], v[226:229], v[202:205], v[34:49]
	ds_read_b128 v[190:193], v178 offset:13888
	s_waitcnt vmcnt(7)
	ds_write_b128 v180, v[154:157] offset:55296
	global_load_dwordx4 v[154:157], v208, s[100:101]
	s_waitcnt lgkmcnt(11)
	v_mfma_f32_32x32x16_bf16 v[18:33], v[230:233], v[234:237], v[18:33]
	v_mfma_f32_32x32x16_bf16 v[2:17], v[230:233], v[202:205], v[2:17]
	s_waitcnt vmcnt(7)
	ds_write_b128 v180, v[158:161] offset:64512
	global_load_dwordx4 v[158:161], v238, s[100:101]
	v_subrev_u32_e32 v180, s20, v180
	s_waitcnt lgkmcnt(8)
	v_mfma_f32_32x32x16_bf16 v[114:129], v[166:169], v[194:197], v[114:129]
	ds_read_b128 v[234:237], v179 offset:36960
	s_waitcnt lgkmcnt(7)
	v_mfma_f32_32x32x16_bf16 v[98:113], v[166:169], v[198:201], v[98:113]
	ds_read_b128 v[218:221], v178 offset:96
	s_waitcnt lgkmcnt(7)
	v_mfma_f32_32x32x16_bf16 v[82:97], v[170:173], v[194:197], v[82:97]
	ds_read_b128 v[202:205], v179 offset:41568
	v_mfma_f32_32x32x16_bf16 v[66:81], v[170:173], v[198:201], v[66:81]
	ds_read_b128 v[222:225], v178 offset:4704
	s_waitcnt lgkmcnt(7)
	v_mfma_f32_32x32x16_bf16 v[50:65], v[174:177], v[194:197], v[50:65]
	ds_read_b128 v[226:229], v178 offset:9312
	v_mfma_f32_32x32x16_bf16 v[34:49], v[174:177], v[198:201], v[34:49]
	ds_read_b128 v[230:233], v178 offset:13920
	v_add_u32_e32 v178, s20, v178
	v_add_u32_e32 v179, s20, v179
	s_waitcnt lgkmcnt(8)
	v_mfma_f32_32x32x16_bf16 v[18:33], v[190:193], v[194:197], v[18:33]
	v_mfma_f32_32x32x16_bf16 v[2:17], v[190:193], v[198:201], v[2:17]
	s_sub_u32 s20, 0, s20
	s_add_u32 s98, s98, 0x80
	s_addc_u32 s99, s99, 0
	s_add_u32 s100, s100, 0x80
	s_addc_u32 s101, s101, 0
	s_waitcnt lgkmcnt(0)
; #define G5_LOAD(k0)                                                                 \
;   {                                                                                 \
;     _Pragma("unroll") for (int i_ = 0; i_ < 4; ++i_) ra[i_] = ldg16(Ap + (size_t)(i_ * 64) * lda + (k0)); \
;     _Pragma("unroll") for (int i_ = 0; i_ < 4; ++i_) rb[i_] = ldg16(Bp + (size_t)(i_ * 64) * ldb + (k0)); \
;   }
; #define G5_STORE(s)                                                                 \
;   {                                                                                 \
;     _Pragma("unroll") for (int i_ = 0; i_ < 4; ++i_) *(u32x4*)(Sw + (s) * STG + i_ * 64 * GS) = ra[i_]; \
;     _Pragma("unroll") for (int i_ = 0; i_ < 4; ++i_) *(u32x4*)(Sw + (s) * STG + 256 * GS + i_ * 64 * GS) = rb[i_]; \
;   }
; template <typename Epi>
; DI void gemm_tile512(const u16* __restrict__ A, int lda, const u16* __restrict__ Bt, int ldb, int K, char* lds_all, Epi epi) {
;     ...
;   const int nk = K >> 6;
;   __syncthreads();
;   G5_LOAD(0);
;   G5_STORE(0);
;   G5_LOAD(64);
;   __syncthreads();
;   for (int kt = 0; kt + 2 < nk; ++kt) {
;     const int cur = kt & 1;
;     G5_COMPUTE(cur);
;     G5_STORE(cur ^ 1);
;     G5_LOAD((kt + 2) << 6);
;     __syncthreads();
;   }
.Lgemm_loop_m1_0:
	s_barrier
	ds_read_b128 v[194:197], v179 offset:36864
	ds_read_b128 v[166:169], v178
	v_mfma_f32_32x32x16_bf16 v[114:129], v[218:221], v[234:237], v[114:129]
	ds_read_b128 v[198:201], v179 offset:41472
	v_mfma_f32_32x32x16_bf16 v[98:113], v[218:221], v[202:205], v[98:113]
	ds_read_b128 v[170:173], v178 offset:4608
	v_mfma_f32_32x32x16_bf16 v[82:97], v[222:225], v[234:237], v[82:97]
	ds_read_b128 v[174:177], v178 offset:9216
	v_mfma_f32_32x32x16_bf16 v[66:81], v[222:225], v[202:205], v[66:81]
	ds_read_b128 v[190:193], v178 offset:13824
	v_mfma_f32_32x32x16_bf16 v[50:65], v[226:229], v[234:237], v[50:65]
	v_mfma_f32_32x32x16_bf16 v[34:49], v[226:229], v[202:205], v[34:49]
	v_mfma_f32_32x32x16_bf16 v[18:33], v[230:233], v[234:237], v[18:33]
	v_mfma_f32_32x32x16_bf16 v[2:17], v[230:233], v[202:205], v[2:17]
	s_waitcnt lgkmcnt(4)
	v_mfma_f32_32x32x16_bf16 v[114:129], v[166:169], v[194:197], v[114:129]
	ds_read_b128 v[234:237], v179 offset:36896
	s_waitcnt lgkmcnt(4)
	v_mfma_f32_32x32x16_bf16 v[98:113], v[166:169], v[198:201], v[98:113]
	ds_read_b128 v[218:221], v178 offset:32
	s_waitcnt vmcnt(7)
	ds_write_b128 v180, v[130:133]
	global_load_dwordx4 v[130:133], v206, s[98:99]
	s_waitcnt lgkmcnt(5)
	v_mfma_f32_32x32x16_bf16 v[82:97], v[170:173], v[194:197], v[82:97]
	ds_read_b128 v[202:205], v179 offset:41504
	v_mfma_f32_32x32x16_bf16 v[66:81], v[170:173], v[198:201], v[66:81]
	ds_read_b128 v[222:225], v178 offset:4640
	s_waitcnt vmcnt(7)
	ds_write_b128 v180, v[134:137] offset:9216
	global_load_dwordx4 v[134:137], v207, s[98:99]
	s_waitcnt lgkmcnt(7)
	v_mfma_f32_32x32x16_bf16 v[50:65], v[174:177], v[194:197], v[50:65]
	ds_read_b128 v[226:229], v178 offset:9248
	v_mfma_f32_32x32x16_bf16 v[34:49], v[174:177], v[198:201], v[34:49]
	ds_read_b128 v[230:233], v178 offset:13856
	s_waitcnt vmcnt(7)
	ds_write_b128 v180, v[138:141] offset:18432
	global_load_dwordx4 v[138:141], v208, s[98:99]
	s_waitcnt lgkmcnt(9)
	v_mfma_f32_32x32x16_bf16 v[18:33], v[190:193], v[194:197], v[18:33]
	v_mfma_f32_32x32x16_bf16 v[2:17], v[190:193], v[198:201], v[2:17]
	s_waitcnt vmcnt(7)
	ds_write_b128 v180, v[142:145] offset:27648
	global_load_dwordx4 v[142:145], v238, s[98:99]
	s_waitcnt lgkmcnt(8)
	v_mfma_f32_32x32x16_bf16 v[114:129], v[218:221], v[234:237], v[114:129]
	ds_read_b128 v[194:197], v179 offset:36928
	s_waitcnt lgkmcnt(7)
	v_mfma_f32_32x32x16_bf16 v[98:113], v[218:221], v[202:205], v[98:113]
	ds_read_b128 v[166:169], v178 offset:64
	s_waitcnt vmcnt(7)
	ds_write_b128 v180, v[146:149] offset:36864
	global_load_dwordx4 v[146:149], v206, s[100:101]
	s_waitcnt lgkmcnt(8)
	v_mfma_f32_32x32x16_bf16 v[82:97], v[222:225], v[234:237], v[82:97]
	ds_read_b128 v[198:201], v179 offset:41536
	v_mfma_f32_32x32x16_bf16 v[66:81], v[222:225], v[202:205], v[66:81]
	ds_read_b128 v[170:173], v178 offset:4672
	s_waitcnt vmcnt(7)
	ds_write_b128 v180, v[150:153] offset:46080
	global_load_dwordx4 v[150:153], v207, s[100:101]
	s_waitcnt lgkmcnt(9)
	v_mfma_f32_32x32x16_bf16 v[50:65], v[226:229], v[234:237], v[50:65]
	ds_read_b128 v[174:177], v178 offset:9280
	v_mfma_f32_32x32x16_bf16 v[34:49], v[226:229], v[202:205], v[34:49]
	ds_read_b128 v[190:193], v178 offset:13888
	s_waitcnt vmcnt(7)
	ds_write_b128 v180, v[154:157] offset:55296
	global_load_dwordx4 v[154:157], v208, s[100:101]
	s_waitcnt lgkmcnt(11)
	v_mfma_f32_32x32x16_bf16 v[18:33], v[230:233], v[234:237], v[18:33]
	v_mfma_f32_32x32x16_bf16 v[2:17], v[230:233], v[202:205], v[2:17]
	s_waitcnt vmcnt(7)
	ds_write_b128 v180, v[158:161] offset:64512
	global_load_dwordx4 v[158:161], v238, s[100:101]
	v_subrev_u32_e32 v180, s20, v180
	s_waitcnt lgkmcnt(8)
	v_mfma_f32_32x32x16_bf16 v[114:129], v[166:169], v[194:197], v[114:129]
	ds_read_b128 v[234:237], v179 offset:36960
	s_waitcnt lgkmcnt(7)
	v_mfma_f32_32x32x16_bf16 v[98:113], v[166:169], v[198:201], v[98:113]
	ds_read_b128 v[218:221], v178 offset:96
	s_waitcnt lgkmcnt(7)
	v_mfma_f32_32x32x16_bf16 v[82:97], v[170:173], v[194:197], v[82:97]
	ds_read_b128 v[202:205], v179 offset:41568
	v_mfma_f32_32x32x16_bf16 v[66:81], v[170:173], v[198:201], v[66:81]
	ds_read_b128 v[222:225], v178 offset:4704
	s_waitcnt lgkmcnt(7)
	v_mfma_f32_32x32x16_bf16 v[50:65], v[174:177], v[194:197], v[50:65]
	ds_read_b128 v[226:229], v178 offset:9312
	v_mfma_f32_32x32x16_bf16 v[34:49], v[174:177], v[198:201], v[34:49]
	ds_read_b128 v[230:233], v178 offset:13920
	v_add_u32_e32 v178, s20, v178
	v_add_u32_e32 v179, s20, v179
	s_waitcnt lgkmcnt(8)
	v_mfma_f32_32x32x16_bf16 v[18:33], v[190:193], v[194:197], v[18:33]
	v_mfma_f32_32x32x16_bf16 v[2:17], v[190:193], v[198:201], v[2:17]
	s_sub_u32 s20, 0, s20
	s_add_u32 s98, s98, 0x80
	s_addc_u32 s99, s99, 0
	s_add_u32 s100, s100, 0x80
	s_addc_u32 s101, s101, 0
	s_waitcnt lgkmcnt(0)
	s_sub_u32 s21, s21, 1
	s_cmp_lg_u32 s21, 0
	s_cbranch_scc1 .Lgemm_loop_m1_0
	s_barrier
; #define G5_STORE(s)                                                                 \
;   {                                                                                 \
;     _Pragma("unroll") for (int i_ = 0; i_ < 4; ++i_) *(u32x4*)(Sw + (s) * STG + i_ * 64 * GS) = ra[i_]; \
;     _Pragma("unroll") for (int i_ = 0; i_ < 4; ++i_) *(u32x4*)(Sw + (s) * STG + 256 * GS + i_ * 64 * GS) = rb[i_]; \
;   }
; template <typename Epi>
; DI void gemm_tile512(const u16* __restrict__ A, int lda, const u16* __restrict__ Bt, int ldb, int K, char* lds_all, Epi epi) {
;     ...
;   {
;     const int cur = (nk - 2) & 1;
;     G5_COMPUTE(cur);
;     G5_STORE(cur ^ 1);
;     __syncthreads();
	ds_read_b128 v[194:197], v179 offset:36864
	ds_read_b128 v[166:169], v178
	v_mfma_f32_32x32x16_bf16 v[114:129], v[218:221], v[234:237], v[114:129]
	ds_read_b128 v[198:201], v179 offset:41472
	v_mfma_f32_32x32x16_bf16 v[98:113], v[218:221], v[202:205], v[98:113]
	ds_read_b128 v[170:173], v178 offset:4608
	v_mfma_f32_32x32x16_bf16 v[82:97], v[222:225], v[234:237], v[82:97]
	ds_read_b128 v[174:177], v178 offset:9216
	v_mfma_f32_32x32x16_bf16 v[66:81], v[222:225], v[202:205], v[66:81]
	ds_read_b128 v[190:193], v178 offset:13824
	v_mfma_f32_32x32x16_bf16 v[50:65], v[226:229], v[234:237], v[50:65]
	v_mfma_f32_32x32x16_bf16 v[34:49], v[226:229], v[202:205], v[34:49]
	v_mfma_f32_32x32x16_bf16 v[18:33], v[230:233], v[234:237], v[18:33]
	v_mfma_f32_32x32x16_bf16 v[2:17], v[230:233], v[202:205], v[2:17]
	s_waitcnt lgkmcnt(4)
	v_mfma_f32_32x32x16_bf16 v[114:129], v[166:169], v[194:197], v[114:129]
	ds_read_b128 v[234:237], v179 offset:36896
	s_waitcnt lgkmcnt(4)
	v_mfma_f32_32x32x16_bf16 v[98:113], v[166:169], v[198:201], v[98:113]
	ds_read_b128 v[218:221], v178 offset:32
	s_waitcnt vmcnt(7)
	ds_write_b128 v180, v[130:133]
	s_waitcnt lgkmcnt(5)
	v_mfma_f32_32x32x16_bf16 v[82:97], v[170:173], v[194:197], v[82:97]
	ds_read_b128 v[202:205], v179 offset:41504
	v_mfma_f32_32x32x16_bf16 v[66:81], v[170:173], v[198:201], v[66:81]
	ds_read_b128 v[222:225], v178 offset:4640
	s_waitcnt vmcnt(6)
	ds_write_b128 v180, v[134:137] offset:9216
	s_waitcnt lgkmcnt(7)
	v_mfma_f32_32x32x16_bf16 v[50:65], v[174:177], v[194:197], v[50:65]
	ds_read_b128 v[226:229], v178 offset:9248
	v_mfma_f32_32x32x16_bf16 v[34:49], v[174:177], v[198:201], v[34:49]
	ds_read_b128 v[230:233], v178 offset:13856
	s_waitcnt vmcnt(5)
	ds_write_b128 v180, v[138:141] offset:18432
	s_waitcnt lgkmcnt(9)
	v_mfma_f32_32x32x16_bf16 v[18:33], v[190:193], v[194:197], v[18:33]
	v_mfma_f32_32x32x16_bf16 v[2:17], v[190:193], v[198:201], v[2:17]
	s_waitcnt vmcnt(4)
	ds_write_b128 v180, v[142:145] offset:27648
	s_waitcnt lgkmcnt(8)
	v_mfma_f32_32x32x16_bf16 v[114:129], v[218:221], v[234:237], v[114:129]
	ds_read_b128 v[194:197], v179 offset:36928
	s_waitcnt lgkmcnt(7)
	v_mfma_f32_32x32x16_bf16 v[98:113], v[218:221], v[202:205], v[98:113]
	ds_read_b128 v[166:169], v178 offset:64
	s_waitcnt vmcnt(3)
	ds_write_b128 v180, v[146:149] offset:36864
	s_waitcnt lgkmcnt(8)
	v_mfma_f32_32x32x16_bf16 v[82:97], v[222:225], v[234:237], v[82:97]
	ds_read_b128 v[198:201], v179 offset:41536
	v_mfma_f32_32x32x16_bf16 v[66:81], v[222:225], v[202:205], v[66:81]
	ds_read_b128 v[170:173], v178 offset:4672
	s_waitcnt vmcnt(2)
	ds_write_b128 v180, v[150:153] offset:46080
	s_waitcnt lgkmcnt(9)
	v_mfma_f32_32x32x16_bf16 v[50:65], v[226:229], v[234:237], v[50:65]
	ds_read_b128 v[174:177], v178 offset:9280
	v_mfma_f32_32x32x16_bf16 v[34:49], v[226:229], v[202:205], v[34:49]
	ds_read_b128 v[190:193], v178 offset:13888
	s_waitcnt vmcnt(1)
	ds_write_b128 v180, v[154:157] offset:55296
	s_waitcnt lgkmcnt(11)
	v_mfma_f32_32x32x16_bf16 v[18:33], v[230:233], v[234:237], v[18:33]
	v_mfma_f32_32x32x16_bf16 v[2:17], v[230:233], v[202:205], v[2:17]
	s_waitcnt vmcnt(0)
	ds_write_b128 v180, v[158:161] offset:64512
	v_subrev_u32_e32 v180, s20, v180
	s_waitcnt lgkmcnt(8)
	v_mfma_f32_32x32x16_bf16 v[114:129], v[166:169], v[194:197], v[114:129]
	ds_read_b128 v[234:237], v179 offset:36960
	s_waitcnt lgkmcnt(7)
	v_mfma_f32_32x32x16_bf16 v[98:113], v[166:169], v[198:201], v[98:113]
	ds_read_b128 v[218:221], v178 offset:96
	s_waitcnt lgkmcnt(7)
	v_mfma_f32_32x32x16_bf16 v[82:97], v[170:173], v[194:197], v[82:97]
	ds_read_b128 v[202:205], v179 offset:41568
	v_mfma_f32_32x32x16_bf16 v[66:81], v[170:173], v[198:201], v[66:81]
	ds_read_b128 v[222:225], v178 offset:4704
	s_waitcnt lgkmcnt(7)
	v_mfma_f32_32x32x16_bf16 v[50:65], v[174:177], v[194:197], v[50:65]
	ds_read_b128 v[226:229], v178 offset:9312
	v_mfma_f32_32x32x16_bf16 v[34:49], v[174:177], v[198:201], v[34:49]
	ds_read_b128 v[230:233], v178 offset:13920
	v_add_u32_e32 v178, s20, v178
	v_add_u32_e32 v179, s20, v179
	s_waitcnt lgkmcnt(8)
	v_mfma_f32_32x32x16_bf16 v[18:33], v[190:193], v[194:197], v[18:33]
	v_mfma_f32_32x32x16_bf16 v[2:17], v[190:193], v[198:201], v[2:17]
	s_sub_u32 s20, 0, s20
	s_waitcnt lgkmcnt(0)
	s_barrier
; template <typename Epi>
; DI void gemm_tile512(const u16* __restrict__ A, int lda, const u16* __restrict__ Bt, int ldb, int K, char* lds_all, Epi epi) {
;     ...
;     G5_COMPUTE(cur ^ 1);
	ds_read_b128 v[194:197], v179 offset:36864
	ds_read_b128 v[166:169], v178
	v_mfma_f32_32x32x16_bf16 v[114:129], v[218:221], v[234:237], v[114:129]
	ds_read_b128 v[198:201], v179 offset:41472
	v_mfma_f32_32x32x16_bf16 v[98:113], v[218:221], v[202:205], v[98:113]
	ds_read_b128 v[170:173], v178 offset:4608
	v_mfma_f32_32x32x16_bf16 v[82:97], v[222:225], v[234:237], v[82:97]
	ds_read_b128 v[174:177], v178 offset:9216
	v_mfma_f32_32x32x16_bf16 v[66:81], v[222:225], v[202:205], v[66:81]
	ds_read_b128 v[190:193], v178 offset:13824
	v_mfma_f32_32x32x16_bf16 v[50:65], v[226:229], v[234:237], v[50:65]
	v_mfma_f32_32x32x16_bf16 v[34:49], v[226:229], v[202:205], v[34:49]
	v_mfma_f32_32x32x16_bf16 v[18:33], v[230:233], v[234:237], v[18:33]
	v_mfma_f32_32x32x16_bf16 v[2:17], v[230:233], v[202:205], v[2:17]
	s_waitcnt lgkmcnt(4)
	v_mfma_f32_32x32x16_bf16 v[114:129], v[166:169], v[194:197], v[114:129]
	ds_read_b128 v[234:237], v179 offset:36896
	s_waitcnt lgkmcnt(4)
	v_mfma_f32_32x32x16_bf16 v[98:113], v[166:169], v[198:201], v[98:113]
	ds_read_b128 v[218:221], v178 offset:32
	s_waitcnt lgkmcnt(4)
	v_mfma_f32_32x32x16_bf16 v[82:97], v[170:173], v[194:197], v[82:97]
	ds_read_b128 v[202:205], v179 offset:41504
	v_mfma_f32_32x32x16_bf16 v[66:81], v[170:173], v[198:201], v[66:81]
	ds_read_b128 v[222:225], v178 offset:4640
	s_waitcnt lgkmcnt(5)
	v_mfma_f32_32x32x16_bf16 v[50:65], v[174:177], v[194:197], v[50:65]
	ds_read_b128 v[226:229], v178 offset:9248
	v_mfma_f32_32x32x16_bf16 v[34:49], v[174:177], v[198:201], v[34:49]
	ds_read_b128 v[230:233], v178 offset:13856
	s_waitcnt lgkmcnt(6)
	v_mfma_f32_32x32x16_bf16 v[18:33], v[190:193], v[194:197], v[18:33]
	v_mfma_f32_32x32x16_bf16 v[2:17], v[190:193], v[198:201], v[2:17]
	s_waitcnt lgkmcnt(4)
	v_mfma_f32_32x32x16_bf16 v[114:129], v[218:221], v[234:237], v[114:129]
	ds_read_b128 v[194:197], v179 offset:36928
	s_waitcnt lgkmcnt(4)
	v_mfma_f32_32x32x16_bf16 v[98:113], v[218:221], v[202:205], v[98:113]
	ds_read_b128 v[166:169], v178 offset:64
	s_waitcnt lgkmcnt(4)
	v_mfma_f32_32x32x16_bf16 v[82:97], v[222:225], v[234:237], v[82:97]
	ds_read_b128 v[198:201], v179 offset:41536
	v_mfma_f32_32x32x16_bf16 v[66:81], v[222:225], v[202:205], v[66:81]
	ds_read_b128 v[170:173], v178 offset:4672
	s_waitcnt lgkmcnt(5)
	v_mfma_f32_32x32x16_bf16 v[50:65], v[226:229], v[234:237], v[50:65]
	ds_read_b128 v[174:177], v178 offset:9280
	v_mfma_f32_32x32x16_bf16 v[34:49], v[226:229], v[202:205], v[34:49]
	ds_read_b128 v[190:193], v178 offset:13888
	s_waitcnt lgkmcnt(6)
	v_mfma_f32_32x32x16_bf16 v[18:33], v[230:233], v[234:237], v[18:33]
	v_mfma_f32_32x32x16_bf16 v[2:17], v[230:233], v[202:205], v[2:17]
	s_waitcnt lgkmcnt(4)
	v_mfma_f32_32x32x16_bf16 v[114:129], v[166:169], v[194:197], v[114:129]
	ds_read_b128 v[234:237], v179 offset:36960
	s_waitcnt lgkmcnt(4)
	v_mfma_f32_32x32x16_bf16 v[98:113], v[166:169], v[198:201], v[98:113]
	ds_read_b128 v[218:221], v178 offset:96
	s_waitcnt lgkmcnt(4)
	v_mfma_f32_32x32x16_bf16 v[82:97], v[170:173], v[194:197], v[82:97]
	ds_read_b128 v[202:205], v179 offset:41568
	v_mfma_f32_32x32x16_bf16 v[66:81], v[170:173], v[198:201], v[66:81]
	ds_read_b128 v[222:225], v178 offset:4704
	s_waitcnt lgkmcnt(5)
	v_mfma_f32_32x32x16_bf16 v[50:65], v[174:177], v[194:197], v[50:65]
	ds_read_b128 v[226:229], v178 offset:9312
	v_mfma_f32_32x32x16_bf16 v[34:49], v[174:177], v[198:201], v[34:49]
	ds_read_b128 v[230:233], v178 offset:13920
	s_waitcnt lgkmcnt(6)
	v_mfma_f32_32x32x16_bf16 v[18:33], v[190:193], v[194:197], v[18:33]
	v_mfma_f32_32x32x16_bf16 v[2:17], v[190:193], v[198:201], v[2:17]
	s_waitcnt lgkmcnt(0)
; DI int crow(int reg, int h) { return (reg & 3) + 8 * (reg >> 2) + 4 * h; }
; template <typename Epi>
; DI void gemm_tile512(const u16* __restrict__ A, int lda, const u16* __restrict__ Bt, int ldb, int K, char* lds_all, Epi epi) {
;     ...
; #pragma unroll 1
;   for (int half = 0; half < 2; ++half) {
;     __syncthreads();
;     if (wm == half) {
; #pragma unroll
;       for (int i = 0; i < 4; ++i)
; #pragma unroll
;         for (int j = 0; j < 2; ++j)
; #pragma unroll
;           for (int g = 0; g < 16; ++g) Cs[(i * 32 + crow(g, h)) * CSW + wn * 64 + j * 32 + r] = acc[i][j][g];
	v_mfma_f32_32x32x16_bf16 v[114:129], v[218:221], v[234:237], v[114:129]
	v_mfma_f32_32x32x16_bf16 v[98:113], v[218:221], v[202:205], v[98:113]
	v_mfma_f32_32x32x16_bf16 v[82:97], v[222:225], v[234:237], v[82:97]
	v_mfma_f32_32x32x16_bf16 v[66:81], v[222:225], v[202:205], v[66:81]
	v_mfma_f32_32x32x16_bf16 v[50:65], v[226:229], v[234:237], v[50:65]
	v_mfma_f32_32x32x16_bf16 v[34:49], v[226:229], v[202:205], v[34:49]
	v_mfma_f32_32x32x16_bf16 v[18:33], v[230:233], v[234:237], v[18:33]
	v_mfma_f32_32x32x16_bf16 v[2:17], v[230:233], v[202:205], v[2:17]
	v_mov_b32_e32 v190, 0x10c20
	v_mov_b32_e32 v191, 0x11040
	v_mov_b32_e32 v192, 0x11460
	v_mov_b32_e32 v193, 0x12900
	v_mov_b32_e32 v194, 0x12d20
	v_mov_b32_e32 v195, 0x13140
	v_mov_b32_e32 v196, 0x13560
	v_mov_b32_e32 v197, 0x14a00
	v_mov_b32_e32 v198, 0x14e20
	v_mov_b32_e32 v199, 0x15240
	v_mov_b32_e32 v200, 0x15660
	v_mov_b32_e32 v201, 0x16b00
	v_mov_b32_e32 v202, 0x16f20
	v_mov_b32_e32 v203, 0x17340
	v_mov_b32_e32 v204, 0x17760
	v_mov_b32_e32 v205, 0x18c00
	v_mov_b32_e32 v206, 0x19020
	v_mov_b32_e32 v207, 0x19440
	v_mov_b32_e32 v208, 0x10800
	v_lshrrev_b32_e32 v218, 8, v165
	v_bfe_u32 v219, v165, 5, 1
	v_and_b32_e32 v220, 31, v165
	v_bfe_u32 v221, v165, 6, 2
	s_mov_b32 s16, 0
	s_movk_i32 s12, 0x1080
	v_mad_u32_u24 v172, v219, s12, v242
	v_mad_u32_u24 v173, v219, s12, v243
	v_mad_u32_u24 v174, v219, s12, v244
	v_mad_u32_u24 v175, v219, s12, v245
	v_mad_u32_u24 v176, v219, s12, v246
	v_mad_u32_u24 v177, v219, s12, v247
	v_lshlrev_b32_e32 v0, 8, v221
	v_lshl_or_b32 v130, v220, 2, v0
	v_mad_u32_u24 v131, v219, s12, v208
	v_mad_u32_u24 v132, v219, s12, v190
	v_mad_u32_u24 v133, v219, s12, v191
	v_mad_u32_u24 v0, v219, s12, v130
	v_add_u32_e32 v154, v130, v133
	v_add_u32_e32 v224, v130, v172
	v_add_u32_e32 v225, v130, v173
	v_add_u32_e32 v226, v130, v174
	v_add_u32_e32 v227, v130, v175
	v_add_u32_e32 v228, v130, v176
	v_add_u32_e32 v229, v130, v177
	v_mad_u32_u24 v134, v219, s12, v192
	v_mad_u32_u24 v135, v219, s12, v193
	v_mad_u32_u24 v136, v219, s12, v194
	v_mad_u32_u24 v137, v219, s12, v195
	v_add_u32_e32 v155, v130, v134
	v_add_u32_e32 v156, v130, v135
	v_add_u32_e32 v157, v130, v136
	v_add_u32_e32 v158, v130, v137
	v_mad_u32_u24 v138, v219, s12, v196
	v_mad_u32_u24 v139, v219, s12, v197
	v_mad_u32_u24 v140, v219, s12, v198
	v_mad_u32_u24 v141, v219, s12, v199
	v_add_u32_e32 v159, v130, v138
	v_add_u32_e32 v160, v130, v139
	v_add_u32_e32 v161, v130, v140
	v_mad_u32_u24 v146, v219, s12, v204
	v_mad_u32_u24 v147, v219, s12, v205
	v_mad_u32_u24 v148, v219, s12, v206
	v_mad_u32_u24 v149, v219, s12, v207
	v_add_u32_e32 v166, v130, v141
	v_add_u32_e32 v171, v130, v146
	v_add_u32_e32 v220, v130, v148
	v_mov_b32_e32 v152, 0x1da60
	v_mad_u32_u24 v178, v219, s12, v152
	v_mov_b32_e32 v152, 0x1ef00
	v_mad_u32_u24 v179, v219, s12, v152
	v_mov_b32_e32 v152, 0x1f320
	v_mad_u32_u24 v180, v219, s12, v152
	v_mov_b32_e32 v152, 0x1f740
	v_mad_u32_u24 v181, v219, s12, v152
	v_mov_b32_e32 v152, 0x1fb60
	v_mad_u32_u24 v142, v219, s12, v200
	v_mad_u32_u24 v143, v219, s12, v201
	v_mad_u32_u24 v144, v219, s12, v202
	v_mad_u32_u24 v145, v219, s12, v203
	v_mad_u32_u24 v150, v219, s12, v240
	v_mad_u32_u24 v151, v219, s12, v241
	v_mad_u32_u24 v182, v219, s12, v152
	s_mov_b64 s[12:13], -1
	v_add_u32_e32 v152, v130, v131
	v_add_u32_e32 v153, v130, v132
	v_add_u32_e32 v167, v130, v142
	v_add_u32_e32 v168, v130, v143
	v_add_u32_e32 v169, v130, v144
	v_add_u32_e32 v170, v130, v145
	v_add_u32_e32 v219, v130, v147
	v_add_u32_e32 v221, v130, v149
	v_add_u32_e32 v222, v130, v150
	v_add_u32_e32 v223, v130, v151
	v_add_u32_e32 v230, v130, v178
	v_add_u32_e32 v231, v130, v179
	v_add_u32_e32 v232, v130, v180
	v_add_u32_e32 v233, v130, v181
	v_add_u32_e32 v234, v130, v182
	s_branch .LBB0_793

; #define G5_LOAD(k0)                                                                 \
;   {                                                                                 \
;     _Pragma("unroll") for (int i_ = 0; i_ < 4; ++i_) ra[i_] = ldg16(Ap + (size_t)(i_ * 64) * lda + (k0)); \
;     _Pragma("unroll") for (int i_ = 0; i_ < 4; ++i_) rb[i_] = ldg16(Bp + (size_t)(i_ * 64) * ldb + (k0)); \
;   }
; #define G5_STORE(s)                                                                 \
;   {                                                                                 \
;     _Pragma("unroll") for (int i_ = 0; i_ < 4; ++i_) *(u32x4*)(Sw + (s) * STG + i_ * 64 * GS) = ra[i_]; \
;     _Pragma("unroll") for (int i_ = 0; i_ < 4; ++i_) *(u32x4*)(Sw + (s) * STG + 256 * GS + i_ * 64 * GS) = rb[i_]; \
;   }
; template <typename Epi>
; DI void gemm_tile512(const u16* __restrict__ A, int lda, const u16* __restrict__ Bt, int ldb, int K, char* lds_all, Epi epi) {
;     ...
;   const int lrow = tid >> 3, lcol = (tid & 7) * 8;
;   const u16* Ap = A + (size_t)lrow * lda + lcol;
;   const u16* Bp = Bt + (size_t)lrow * ldb + lcol;
;   u16* Sw = S0 + lrow * GS + lcol;
;   u32x4 ra[4], rb[4];
;     ...
;   const int nk = K >> 6;
;   __syncthreads();
;   G5_LOAD(0);
;   G5_STORE(0);
;   G5_LOAD(64);
;   __syncthreads();
;   for (int kt = 0; kt + 2 < nk; ++kt) {
;     const int cur = kt & 1;
;     G5_COMPUTE(cur);
;     G5_STORE(cur ^ 1);
;     G5_LOAD((kt + 2) << 6);
;     __syncthreads();
;   }
.LBB0_833:
	s_lshl_b32 s11, s5, 9
	s_lshl_b32 s5, s21, 8
	s_and_b32 s5, s5, 0x100
	s_lshl_b32 s24, s4, 12
	s_lshl_b32 s4, s21, 7
	s_or_b32 s22, s5, s11
	s_sub_i32 s4, s4, s24
	s_and_b32 s23, s4, 0xffffff00
	s_mul_i32 s4, s22, 0x900
	v_readlane_b32 s8, v250, 46
	s_mul_hi_i32 s5, s22, 0x900
	s_add_u32 s4, s8, s4
	v_readlane_b32 s8, v250, 47
	s_addc_u32 s5, s8, s5
	s_mul_i32 s8, s23, 0x900
	s_mul_hi_i32 s9, s23, 0x900
	s_add_u32 s8, s14, s8
	s_addc_u32 s9, s15, s9
	s_mov_b64 s[26:27], s[4:5]
	s_mov_b64 s[98:99], s[26:27]
	s_mov_b64 s[100:101], s[8:9]
	v_lshrrev_b32_e32 v239, 3, v165
	v_and_b32_e32 v0, 7, v165
	v_mul_u32_u24_e32 v206, 0x900, v239
	v_lshl_add_u32 v206, v0, 4, v206
	v_add_u32_e32 v207, 0x24000, v206
	v_add_u32_e32 v208, 0x48000, v206
	v_add_u32_e32 v238, 0x6c000, v206
	v_mul_u32_u24_e32 v180, 0x90, v239
	v_lshl_add_u32 v180, v0, 4, v180
	global_load_dwordx4 v[2:5], v206, s[98:99]
	global_load_dwordx4 v[6:9], v207, s[98:99]
	global_load_dwordx4 v[10:13], v208, s[98:99]
	global_load_dwordx4 v[14:17], v238, s[98:99]
	global_load_dwordx4 v[18:21], v206, s[100:101]
	global_load_dwordx4 v[22:25], v207, s[100:101]
	global_load_dwordx4 v[26:29], v208, s[100:101]
	global_load_dwordx4 v[30:33], v238, s[100:101]
	global_load_dwordx4 v[130:133], v206, s[98:99] offset:128
	global_load_dwordx4 v[134:137], v207, s[98:99] offset:128
	global_load_dwordx4 v[138:141], v208, s[98:99] offset:128
	global_load_dwordx4 v[142:145], v238, s[98:99] offset:128
	global_load_dwordx4 v[146:149], v206, s[100:101] offset:128
	global_load_dwordx4 v[150:153], v207, s[100:101] offset:128
	global_load_dwordx4 v[154:157], v208, s[100:101] offset:128
	global_load_dwordx4 v[158:161], v238, s[100:101] offset:128
	s_add_u32 s98, s98, 0x100
	s_addc_u32 s99, s99, 0
	s_add_u32 s100, s100, 0x100
	s_addc_u32 s101, s101, 0
	v_and_b32_e32 v239, 31, v165
	v_bfe_u32 v0, v165, 5, 1
	v_lshrrev_b32_e32 v179, 8, v165
	v_lshl_or_b32 v178, v179, 7, v239
	v_mul_u32_u24_e32 v178, 0x90, v178
	v_lshl_add_u32 v178, v0, 4, v178
	v_bfe_u32 v179, v165, 6, 2
	v_lshl_or_b32 v179, v179, 6, v239
	v_mul_u32_u24_e32 v179, 0x90, v179
	v_lshl_add_u32 v179, v0, 4, v179
	s_mov_b32 s11, 0x12000
	s_mov_b32 s12, 13
	s_barrier
	s_waitcnt vmcnt(15)
	ds_write_b128 v180, v[2:5]
	s_waitcnt vmcnt(14)
	ds_write_b128 v180, v[6:9] offset:9216
	s_waitcnt vmcnt(13)
	ds_write_b128 v180, v[10:13] offset:18432
	s_waitcnt vmcnt(12)
	ds_write_b128 v180, v[14:17] offset:27648
	s_waitcnt vmcnt(11)
	ds_write_b128 v180, v[18:21] offset:36864
	s_waitcnt vmcnt(10)
	ds_write_b128 v180, v[22:25] offset:46080
	s_waitcnt vmcnt(9)
	ds_write_b128 v180, v[26:29] offset:55296
	s_waitcnt vmcnt(8)
	ds_write_b128 v180, v[30:33] offset:64512
	v_add_u32_e32 v180, 0x12000, v180
	s_waitcnt lgkmcnt(0)
	s_barrier
	ds_read_b128 v[194:197], v179 offset:36864
	ds_read_b128 v[166:169], v178
	ds_read_b128 v[198:201], v179 offset:41472
	ds_read_b128 v[170:173], v178 offset:4608
	ds_read_b128 v[174:177], v178 offset:9216
	ds_read_b128 v[190:193], v178 offset:13824
	s_waitcnt lgkmcnt(4)
	v_mfma_f32_32x32x16_bf16 v[114:129], v[166:169], v[194:197], 0
	ds_read_b128 v[234:237], v179 offset:36896
	s_waitcnt lgkmcnt(4)
	v_mfma_f32_32x32x16_bf16 v[98:113], v[166:169], v[198:201], 0
	ds_read_b128 v[218:221], v178 offset:32
	s_waitcnt vmcnt(7)
	ds_write_b128 v180, v[130:133]
	global_load_dwordx4 v[130:133], v206, s[98:99]
	s_waitcnt lgkmcnt(5)
	v_mfma_f32_32x32x16_bf16 v[82:97], v[170:173], v[194:197], 0
	ds_read_b128 v[202:205], v179 offset:41504
	v_mfma_f32_32x32x16_bf16 v[66:81], v[170:173], v[198:201], 0
	ds_read_b128 v[222:225], v178 offset:4640
	s_waitcnt vmcnt(7)
	ds_write_b128 v180, v[134:137] offset:9216
	global_load_dwordx4 v[134:137], v207, s[98:99]
	s_waitcnt lgkmcnt(7)
	v_mfma_f32_32x32x16_bf16 v[50:65], v[174:177], v[194:197], 0
	ds_read_b128 v[226:229], v178 offset:9248
	v_mfma_f32_32x32x16_bf16 v[34:49], v[174:177], v[198:201], 0
	ds_read_b128 v[230:233], v178 offset:13856
	s_waitcnt vmcnt(7)
	ds_write_b128 v180, v[138:141] offset:18432
	global_load_dwordx4 v[138:141], v208, s[98:99]
	s_waitcnt lgkmcnt(9)
	v_mfma_f32_32x32x16_bf16 v[18:33], v[190:193], v[194:197], 0
	v_mfma_f32_32x32x16_bf16 v[2:17], v[190:193], v[198:201], 0
	s_waitcnt vmcnt(7)
	ds_write_b128 v180, v[142:145] offset:27648
	global_load_dwordx4 v[142:145], v238, s[98:99]
	s_waitcnt lgkmcnt(8)
	v_mfma_f32_32x32x16_bf16 v[114:129], v[218:221], v[234:237], v[114:129]
	ds_read_b128 v[194:197], v179 offset:36928
	s_waitcnt lgkmcnt(7)
	v_mfma_f32_32x32x16_bf16 v[98:113], v[218:221], v[202:205], v[98:113]
	ds_read_b128 v[166:169], v178 offset:64
	s_waitcnt vmcnt(7)
	ds_write_b128 v180, v[146:149] offset:36864
	global_load_dwordx4 v[146:149], v206, s[100:101]
	s_waitcnt lgkmcnt(8)
	v_mfma_f32_32x32x16_bf16 v[82:97], v[222:225], v[234:237], v[82:97]
	ds_read_b128 v[198:201], v179 offset:41536
	v_mfma_f32_32x32x16_bf16 v[66:81], v[222:225], v[202:205], v[66:81]
	ds_read_b128 v[170:173], v178 offset:4672
	s_waitcnt vmcnt(7)
	ds_write_b128 v180, v[150:153] offset:46080
	global_load_dwordx4 v[150:153], v207, s[100:101]
	s_waitcnt lgkmcnt(9)
	v_mfma_f32_32x32x16_bf16 v[50:65], v[226:229], v[234:237], v[50:65]
	ds_read_b128 v[174:177], v178 offset:9280
	v_mfma_f32_32x32x16_bf16 v[34:49], v[226:229], v[202:205], v[34:49]
	ds_read_b128 v[190:193], v178 offset:13888
	s_waitcnt vmcnt(7)
	ds_write_b128 v180, v[154:157] offset:55296
	global_load_dwordx4 v[154:157], v208, s[100:101]
	s_waitcnt lgkmcnt(11)
	v_mfma_f32_32x32x16_bf16 v[18:33], v[230:233], v[234:237], v[18:33]
	v_mfma_f32_32x32x16_bf16 v[2:17], v[230:233], v[202:205], v[2:17]
	s_waitcnt vmcnt(7)
	ds_write_b128 v180, v[158:161] offset:64512
	global_load_dwordx4 v[158:161], v238, s[100:101]
	v_subrev_u32_e32 v180, s11, v180
	s_waitcnt lgkmcnt(8)
	v_mfma_f32_32x32x16_bf16 v[114:129], v[166:169], v[194:197], v[114:129]
	ds_read_b128 v[234:237], v179 offset:36960
	s_waitcnt lgkmcnt(7)
	v_mfma_f32_32x32x16_bf16 v[98:113], v[166:169], v[198:201], v[98:113]
	ds_read_b128 v[218:221], v178 offset:96
	s_waitcnt lgkmcnt(7)
	v_mfma_f32_32x32x16_bf16 v[82:97], v[170:173], v[194:197], v[82:97]
	ds_read_b128 v[202:205], v179 offset:41568
	v_mfma_f32_32x32x16_bf16 v[66:81], v[170:173], v[198:201], v[66:81]
	ds_read_b128 v[222:225], v178 offset:4704
	s_waitcnt lgkmcnt(7)
	v_mfma_f32_32x32x16_bf16 v[50:65], v[174:177], v[194:197], v[50:65]
	ds_read_b128 v[226:229], v178 offset:9312
	v_mfma_f32_32x32x16_bf16 v[34:49], v[174:177], v[198:201], v[34:49]
	ds_read_b128 v[230:233], v178 offset:13920
	v_add_u32_e32 v178, s11, v178
	v_add_u32_e32 v179, s11, v179
	s_waitcnt lgkmcnt(8)
	v_mfma_f32_32x32x16_bf16 v[18:33], v[190:193], v[194:197], v[18:33]
	v_mfma_f32_32x32x16_bf16 v[2:17], v[190:193], v[198:201], v[2:17]
	s_sub_u32 s11, 0, s11
	s_add_u32 s98, s98, 0x80
	s_addc_u32 s99, s99, 0
	s_add_u32 s100, s100, 0x80
	s_addc_u32 s101, s101, 0
	s_waitcnt lgkmcnt(0)
; #define G5_LOAD(k0)                                                                 \
;   {                                                                                 \
;     _Pragma("unroll") for (int i_ = 0; i_ < 4; ++i_) ra[i_] = ldg16(Ap + (size_t)(i_ * 64) * lda + (k0)); \
;     _Pragma("unroll") for (int i_ = 0; i_ < 4; ++i_) rb[i_] = ldg16(Bp + (size_t)(i_ * 64) * ldb + (k0)); \
;   }
; #define G5_STORE(s)                                                                 \
;   {                                                                                 \
;     _Pragma("unroll") for (int i_ = 0; i_ < 4; ++i_) *(u32x4*)(Sw + (s) * STG + i_ * 64 * GS) = ra[i_]; \
;     _Pragma("unroll") for (int i_ = 0; i_ < 4; ++i_) *(u32x4*)(Sw + (s) * STG + 256 * GS + i_ * 64 * GS) = rb[i_]; \
;   }
; template <typename Epi>
; DI void gemm_tile512(const u16* __restrict__ A, int lda, const u16* __restrict__ Bt, int ldb, int K, char* lds_all, Epi epi) {
;     ...
;   const int nk = K >> 6;
;   __syncthreads();
;   G5_LOAD(0);
;   G5_STORE(0);
;   G5_LOAD(64);
;   __syncthreads();
;   for (int kt = 0; kt + 2 < nk; ++kt) {
;     const int cur = kt & 1;
;     G5_COMPUTE(cur);
;     G5_STORE(cur ^ 1);
;     G5_LOAD((kt + 2) << 6);
;     __syncthreads();
;   }
.Lgemm_loop_m2_0:
	s_barrier
	ds_read_b128 v[194:197], v179 offset:36864
	ds_read_b128 v[166:169], v178
	v_mfma_f32_32x32x16_bf16 v[114:129], v[218:221], v[234:237], v[114:129]
	ds_read_b128 v[198:201], v179 offset:41472
	v_mfma_f32_32x32x16_bf16 v[98:113], v[218:221], v[202:205], v[98:113]
	ds_read_b128 v[170:173], v178 offset:4608
	v_mfma_f32_32x32x16_bf16 v[82:97], v[222:225], v[234:237], v[82:97]
	ds_read_b128 v[174:177], v178 offset:9216
	v_mfma_f32_32x32x16_bf16 v[66:81], v[222:225], v[202:205], v[66:81]
	ds_read_b128 v[190:193], v178 offset:13824
	v_mfma_f32_32x32x16_bf16 v[50:65], v[226:229], v[234:237], v[50:65]
	v_mfma_f32_32x32x16_bf16 v[34:49], v[226:229], v[202:205], v[34:49]
	v_mfma_f32_32x32x16_bf16 v[18:33], v[230:233], v[234:237], v[18:33]
	v_mfma_f32_32x32x16_bf16 v[2:17], v[230:233], v[202:205], v[2:17]
	s_waitcnt lgkmcnt(4)
	v_mfma_f32_32x32x16_bf16 v[114:129], v[166:169], v[194:197], v[114:129]
	ds_read_b128 v[234:237], v179 offset:36896
	s_waitcnt lgkmcnt(4)
	v_mfma_f32_32x32x16_bf16 v[98:113], v[166:169], v[198:201], v[98:113]
	ds_read_b128 v[218:221], v178 offset:32
	s_waitcnt vmcnt(7)
	ds_write_b128 v180, v[130:133]
	global_load_dwordx4 v[130:133], v206, s[98:99]
	s_waitcnt lgkmcnt(5)
	v_mfma_f32_32x32x16_bf16 v[82:97], v[170:173], v[194:197], v[82:97]
	ds_read_b128 v[202:205], v179 offset:41504
	v_mfma_f32_32x32x16_bf16 v[66:81], v[170:173], v[198:201], v[66:81]
	ds_read_b128 v[222:225], v178 offset:4640
	s_waitcnt vmcnt(7)
	ds_write_b128 v180, v[134:137] offset:9216
	global_load_dwordx4 v[134:137], v207, s[98:99]
	s_waitcnt lgkmcnt(7)
	v_mfma_f32_32x32x16_bf16 v[50:65], v[174:177], v[194:197], v[50:65]
	ds_read_b128 v[226:229], v178 offset:9248
	v_mfma_f32_32x32x16_bf16 v[34:49], v[174:177], v[198:201], v[34:49]
	ds_read_b128 v[230:233], v178 offset:13856
	s_waitcnt vmcnt(7)
	ds_write_b128 v180, v[138:141] offset:18432
	global_load_dwordx4 v[138:141], v208, s[98:99]
	s_waitcnt lgkmcnt(9)
	v_mfma_f32_32x32x16_bf16 v[18:33], v[190:193], v[194:197], v[18:33]
	v_mfma_f32_32x32x16_bf16 v[2:17], v[190:193], v[198:201], v[2:17]
	s_waitcnt vmcnt(7)
	ds_write_b128 v180, v[142:145] offset:27648
	global_load_dwordx4 v[142:145], v238, s[98:99]
	s_waitcnt lgkmcnt(8)
	v_mfma_f32_32x32x16_bf16 v[114:129], v[218:221], v[234:237], v[114:129]
	ds_read_b128 v[194:197], v179 offset:36928
	s_waitcnt lgkmcnt(7)
	v_mfma_f32_32x32x16_bf16 v[98:113], v[218:221], v[202:205], v[98:113]
	ds_read_b128 v[166:169], v178 offset:64
	s_waitcnt vmcnt(7)
	ds_write_b128 v180, v[146:149] offset:36864
	global_load_dwordx4 v[146:149], v206, s[100:101]
	s_waitcnt lgkmcnt(8)
	v_mfma_f32_32x32x16_bf16 v[82:97], v[222:225], v[234:237], v[82:97]
	ds_read_b128 v[198:201], v179 offset:41536
	v_mfma_f32_32x32x16_bf16 v[66:81], v[222:225], v[202:205], v[66:81]
	ds_read_b128 v[170:173], v178 offset:4672
	s_waitcnt vmcnt(7)
	ds_write_b128 v180, v[150:153] offset:46080
	global_load_dwordx4 v[150:153], v207, s[100:101]
	s_waitcnt lgkmcnt(9)
	v_mfma_f32_32x32x16_bf16 v[50:65], v[226:229], v[234:237], v[50:65]
	ds_read_b128 v[174:177], v178 offset:9280
	v_mfma_f32_32x32x16_bf16 v[34:49], v[226:229], v[202:205], v[34:49]
	ds_read_b128 v[190:193], v178 offset:13888
	s_waitcnt vmcnt(7)
	ds_write_b128 v180, v[154:157] offset:55296
	global_load_dwordx4 v[154:157], v208, s[100:101]
	s_waitcnt lgkmcnt(11)
	v_mfma_f32_32x32x16_bf16 v[18:33], v[230:233], v[234:237], v[18:33]
	v_mfma_f32_32x32x16_bf16 v[2:17], v[230:233], v[202:205], v[2:17]
	s_waitcnt vmcnt(7)
	ds_write_b128 v180, v[158:161] offset:64512
	global_load_dwordx4 v[158:161], v238, s[100:101]
	v_subrev_u32_e32 v180, s11, v180
	s_waitcnt lgkmcnt(8)
	v_mfma_f32_32x32x16_bf16 v[114:129], v[166:169], v[194:197], v[114:129]
	ds_read_b128 v[234:237], v179 offset:36960
	s_waitcnt lgkmcnt(7)
	v_mfma_f32_32x32x16_bf16 v[98:113], v[166:169], v[198:201], v[98:113]
	ds_read_b128 v[218:221], v178 offset:96
	s_waitcnt lgkmcnt(7)
	v_mfma_f32_32x32x16_bf16 v[82:97], v[170:173], v[194:197], v[82:97]
	ds_read_b128 v[202:205], v179 offset:41568
	v_mfma_f32_32x32x16_bf16 v[66:81], v[170:173], v[198:201], v[66:81]
	ds_read_b128 v[222:225], v178 offset:4704
	s_waitcnt lgkmcnt(7)
	v_mfma_f32_32x32x16_bf16 v[50:65], v[174:177], v[194:197], v[50:65]
	ds_read_b128 v[226:229], v178 offset:9312
	v_mfma_f32_32x32x16_bf16 v[34:49], v[174:177], v[198:201], v[34:49]
	ds_read_b128 v[230:233], v178 offset:13920
	v_add_u32_e32 v178, s11, v178
	v_add_u32_e32 v179, s11, v179
	s_waitcnt lgkmcnt(8)
	v_mfma_f32_32x32x16_bf16 v[18:33], v[190:193], v[194:197], v[18:33]
	v_mfma_f32_32x32x16_bf16 v[2:17], v[190:193], v[198:201], v[2:17]
	s_sub_u32 s11, 0, s11
	s_add_u32 s98, s98, 0x80
	s_addc_u32 s99, s99, 0
	s_add_u32 s100, s100, 0x80
	s_addc_u32 s101, s101, 0
	s_waitcnt lgkmcnt(0)
	s_sub_u32 s12, s12, 1
	s_cmp_lg_u32 s12, 0
	s_cbranch_scc1 .Lgemm_loop_m2_0
	s_barrier
; #define G5_STORE(s)                                                                 \
;   {                                                                                 \
;     _Pragma("unroll") for (int i_ = 0; i_ < 4; ++i_) *(u32x4*)(Sw + (s) * STG + i_ * 64 * GS) = ra[i_]; \
;     _Pragma("unroll") for (int i_ = 0; i_ < 4; ++i_) *(u32x4*)(Sw + (s) * STG + 256 * GS + i_ * 64 * GS) = rb[i_]; \
;   }
; template <typename Epi>
; DI void gemm_tile512(const u16* __restrict__ A, int lda, const u16* __restrict__ Bt, int ldb, int K, char* lds_all, Epi epi) {
;     ...
;   {
;     const int cur = (nk - 2) & 1;
;     G5_COMPUTE(cur);
;     G5_STORE(cur ^ 1);
;     __syncthreads();
	ds_read_b128 v[194:197], v179 offset:36864
	ds_read_b128 v[166:169], v178
	v_mfma_f32_32x32x16_bf16 v[114:129], v[218:221], v[234:237], v[114:129]
	ds_read_b128 v[198:201], v179 offset:41472
	v_mfma_f32_32x32x16_bf16 v[98:113], v[218:221], v[202:205], v[98:113]
	ds_read_b128 v[170:173], v178 offset:4608
	v_mfma_f32_32x32x16_bf16 v[82:97], v[222:225], v[234:237], v[82:97]
	ds_read_b128 v[174:177], v178 offset:9216
	v_mfma_f32_32x32x16_bf16 v[66:81], v[222:225], v[202:205], v[66:81]
	ds_read_b128 v[190:193], v178 offset:13824
	v_mfma_f32_32x32x16_bf16 v[50:65], v[226:229], v[234:237], v[50:65]
	v_mfma_f32_32x32x16_bf16 v[34:49], v[226:229], v[202:205], v[34:49]
	v_mfma_f32_32x32x16_bf16 v[18:33], v[230:233], v[234:237], v[18:33]
	v_mfma_f32_32x32x16_bf16 v[2:17], v[230:233], v[202:205], v[2:17]
	s_waitcnt lgkmcnt(4)
	v_mfma_f32_32x32x16_bf16 v[114:129], v[166:169], v[194:197], v[114:129]
	ds_read_b128 v[234:237], v179 offset:36896
	s_waitcnt lgkmcnt(4)
	v_mfma_f32_32x32x16_bf16 v[98:113], v[166:169], v[198:201], v[98:113]
	ds_read_b128 v[218:221], v178 offset:32
	s_waitcnt vmcnt(7)
	ds_write_b128 v180, v[130:133]
	s_waitcnt lgkmcnt(5)
	v_mfma_f32_32x32x16_bf16 v[82:97], v[170:173], v[194:197], v[82:97]
	ds_read_b128 v[202:205], v179 offset:41504
	v_mfma_f32_32x32x16_bf16 v[66:81], v[170:173], v[198:201], v[66:81]
	ds_read_b128 v[222:225], v178 offset:4640
	s_waitcnt vmcnt(6)
	ds_write_b128 v180, v[134:137] offset:9216
	s_waitcnt lgkmcnt(7)
	v_mfma_f32_32x32x16_bf16 v[50:65], v[174:177], v[194:197], v[50:65]
	ds_read_b128 v[226:229], v178 offset:9248
	v_mfma_f32_32x32x16_bf16 v[34:49], v[174:177], v[198:201], v[34:49]
	ds_read_b128 v[230:233], v178 offset:13856
	s_waitcnt vmcnt(5)
	ds_write_b128 v180, v[138:141] offset:18432
	s_waitcnt lgkmcnt(9)
	v_mfma_f32_32x32x16_bf16 v[18:33], v[190:193], v[194:197], v[18:33]
	v_mfma_f32_32x32x16_bf16 v[2:17], v[190:193], v[198:201], v[2:17]
	s_waitcnt vmcnt(4)
	ds_write_b128 v180, v[142:145] offset:27648
	s_waitcnt lgkmcnt(8)
	v_mfma_f32_32x32x16_bf16 v[114:129], v[218:221], v[234:237], v[114:129]
	ds_read_b128 v[194:197], v179 offset:36928
	s_waitcnt lgkmcnt(7)
	v_mfma_f32_32x32x16_bf16 v[98:113], v[218:221], v[202:205], v[98:113]
	ds_read_b128 v[166:169], v178 offset:64
	s_waitcnt vmcnt(3)
	ds_write_b128 v180, v[146:149] offset:36864
	s_waitcnt lgkmcnt(8)
	v_mfma_f32_32x32x16_bf16 v[82:97], v[222:225], v[234:237], v[82:97]
	ds_read_b128 v[198:201], v179 offset:41536
	v_mfma_f32_32x32x16_bf16 v[66:81], v[222:225], v[202:205], v[66:81]
	ds_read_b128 v[170:173], v178 offset:4672
	s_waitcnt vmcnt(2)
	ds_write_b128 v180, v[150:153] offset:46080
	s_waitcnt lgkmcnt(9)
	v_mfma_f32_32x32x16_bf16 v[50:65], v[226:229], v[234:237], v[50:65]
	ds_read_b128 v[174:177], v178 offset:9280
	v_mfma_f32_32x32x16_bf16 v[34:49], v[226:229], v[202:205], v[34:49]
	ds_read_b128 v[190:193], v178 offset:13888
	s_waitcnt vmcnt(1)
	ds_write_b128 v180, v[154:157] offset:55296
	s_waitcnt lgkmcnt(11)
	v_mfma_f32_32x32x16_bf16 v[18:33], v[230:233], v[234:237], v[18:33]
	v_mfma_f32_32x32x16_bf16 v[2:17], v[230:233], v[202:205], v[2:17]
	s_waitcnt vmcnt(0)
	ds_write_b128 v180, v[158:161] offset:64512
	v_subrev_u32_e32 v180, s11, v180
	s_waitcnt lgkmcnt(8)
	v_mfma_f32_32x32x16_bf16 v[114:129], v[166:169], v[194:197], v[114:129]
	ds_read_b128 v[234:237], v179 offset:36960
	s_waitcnt lgkmcnt(7)
	v_mfma_f32_32x32x16_bf16 v[98:113], v[166:169], v[198:201], v[98:113]
	ds_read_b128 v[218:221], v178 offset:96
	s_waitcnt lgkmcnt(7)
	v_mfma_f32_32x32x16_bf16 v[82:97], v[170:173], v[194:197], v[82:97]
	ds_read_b128 v[202:205], v179 offset:41568
	v_mfma_f32_32x32x16_bf16 v[66:81], v[170:173], v[198:201], v[66:81]
	ds_read_b128 v[222:225], v178 offset:4704
	s_waitcnt lgkmcnt(7)
	v_mfma_f32_32x32x16_bf16 v[50:65], v[174:177], v[194:197], v[50:65]
	ds_read_b128 v[226:229], v178 offset:9312
	v_mfma_f32_32x32x16_bf16 v[34:49], v[174:177], v[198:201], v[34:49]
	ds_read_b128 v[230:233], v178 offset:13920
	v_add_u32_e32 v178, s11, v178
	v_add_u32_e32 v179, s11, v179
	s_waitcnt lgkmcnt(8)
	v_mfma_f32_32x32x16_bf16 v[18:33], v[190:193], v[194:197], v[18:33]
	v_mfma_f32_32x32x16_bf16 v[2:17], v[190:193], v[198:201], v[2:17]
	s_sub_u32 s11, 0, s11
	s_waitcnt lgkmcnt(0)
	s_barrier
; template <typename Epi>
; DI void gemm_tile512(const u16* __restrict__ A, int lda, const u16* __restrict__ Bt, int ldb, int K, char* lds_all, Epi epi) {
;     ...
;     G5_COMPUTE(cur ^ 1);
	ds_read_b128 v[194:197], v179 offset:36864
	ds_read_b128 v[166:169], v178
	v_mfma_f32_32x32x16_bf16 v[114:129], v[218:221], v[234:237], v[114:129]
	ds_read_b128 v[198:201], v179 offset:41472
	v_mfma_f32_32x32x16_bf16 v[98:113], v[218:221], v[202:205], v[98:113]
	ds_read_b128 v[170:173], v178 offset:4608
	v_mfma_f32_32x32x16_bf16 v[82:97], v[222:225], v[234:237], v[82:97]
	ds_read_b128 v[174:177], v178 offset:9216
	v_mfma_f32_32x32x16_bf16 v[66:81], v[222:225], v[202:205], v[66:81]
	ds_read_b128 v[190:193], v178 offset:13824
	v_mfma_f32_32x32x16_bf16 v[50:65], v[226:229], v[234:237], v[50:65]
	v_mfma_f32_32x32x16_bf16 v[34:49], v[226:229], v[202:205], v[34:49]
	v_mfma_f32_32x32x16_bf16 v[18:33], v[230:233], v[234:237], v[18:33]
	v_mfma_f32_32x32x16_bf16 v[2:17], v[230:233], v[202:205], v[2:17]
	s_waitcnt lgkmcnt(4)
	v_mfma_f32_32x32x16_bf16 v[114:129], v[166:169], v[194:197], v[114:129]
	ds_read_b128 v[234:237], v179 offset:36896
	s_waitcnt lgkmcnt(4)
	v_mfma_f32_32x32x16_bf16 v[98:113], v[166:169], v[198:201], v[98:113]
	ds_read_b128 v[218:221], v178 offset:32
	s_waitcnt lgkmcnt(4)
	v_mfma_f32_32x32x16_bf16 v[82:97], v[170:173], v[194:197], v[82:97]
	ds_read_b128 v[202:205], v179 offset:41504
	v_mfma_f32_32x32x16_bf16 v[66:81], v[170:173], v[198:201], v[66:81]
	ds_read_b128 v[222:225], v178 offset:4640
	s_waitcnt lgkmcnt(5)
	v_mfma_f32_32x32x16_bf16 v[50:65], v[174:177], v[194:197], v[50:65]
	ds_read_b128 v[226:229], v178 offset:9248
	v_mfma_f32_32x32x16_bf16 v[34:49], v[174:177], v[198:201], v[34:49]
	ds_read_b128 v[230:233], v178 offset:13856
	s_waitcnt lgkmcnt(6)
	v_mfma_f32_32x32x16_bf16 v[18:33], v[190:193], v[194:197], v[18:33]
	v_mfma_f32_32x32x16_bf16 v[2:17], v[190:193], v[198:201], v[2:17]
	s_waitcnt lgkmcnt(4)
	v_mfma_f32_32x32x16_bf16 v[114:129], v[218:221], v[234:237], v[114:129]
	ds_read_b128 v[194:197], v179 offset:36928
	s_waitcnt lgkmcnt(4)
	v_mfma_f32_32x32x16_bf16 v[98:113], v[218:221], v[202:205], v[98:113]
	ds_read_b128 v[166:169], v178 offset:64
	s_waitcnt lgkmcnt(4)
	v_mfma_f32_32x32x16_bf16 v[82:97], v[222:225], v[234:237], v[82:97]
	ds_read_b128 v[198:201], v179 offset:41536
	v_mfma_f32_32x32x16_bf16 v[66:81], v[222:225], v[202:205], v[66:81]
	ds_read_b128 v[170:173], v178 offset:4672
	s_waitcnt lgkmcnt(5)
	v_mfma_f32_32x32x16_bf16 v[50:65], v[226:229], v[234:237], v[50:65]
	ds_read_b128 v[174:177], v178 offset:9280
	v_mfma_f32_32x32x16_bf16 v[34:49], v[226:229], v[202:205], v[34:49]
	ds_read_b128 v[190:193], v178 offset:13888
	s_waitcnt lgkmcnt(6)
	v_mfma_f32_32x32x16_bf16 v[18:33], v[230:233], v[234:237], v[18:33]
	v_mfma_f32_32x32x16_bf16 v[2:17], v[230:233], v[202:205], v[2:17]
	s_waitcnt lgkmcnt(4)
	v_mfma_f32_32x32x16_bf16 v[114:129], v[166:169], v[194:197], v[114:129]
	ds_read_b128 v[234:237], v179 offset:36960
	s_waitcnt lgkmcnt(4)
	v_mfma_f32_32x32x16_bf16 v[98:113], v[166:169], v[198:201], v[98:113]
	ds_read_b128 v[218:221], v178 offset:96
	s_waitcnt lgkmcnt(4)
	v_mfma_f32_32x32x16_bf16 v[82:97], v[170:173], v[194:197], v[82:97]
	ds_read_b128 v[202:205], v179 offset:41568
	v_mfma_f32_32x32x16_bf16 v[66:81], v[170:173], v[198:201], v[66:81]
	ds_read_b128 v[222:225], v178 offset:4704
	s_waitcnt lgkmcnt(5)
	v_mfma_f32_32x32x16_bf16 v[50:65], v[174:177], v[194:197], v[50:65]
	ds_read_b128 v[226:229], v178 offset:9312
	v_mfma_f32_32x32x16_bf16 v[34:49], v[174:177], v[198:201], v[34:49]
	ds_read_b128 v[230:233], v178 offset:13920
	s_waitcnt lgkmcnt(6)
	v_mfma_f32_32x32x16_bf16 v[18:33], v[190:193], v[194:197], v[18:33]
	v_mfma_f32_32x32x16_bf16 v[2:17], v[190:193], v[198:201], v[2:17]
	s_waitcnt lgkmcnt(0)
; DI int crow(int reg, int h) { return (reg & 3) + 8 * (reg >> 2) + 4 * h; }
; template <typename Epi>
; DI void gemm_tile512(const u16* __restrict__ A, int lda, const u16* __restrict__ Bt, int ldb, int K, char* lds_all, Epi epi) {
;     ...
; #pragma unroll 1
;   for (int half = 0; half < 2; ++half) {
;     __syncthreads();
;     if (wm == half) {
; #pragma unroll
;       for (int i = 0; i < 4; ++i)
; #pragma unroll
;         for (int j = 0; j < 2; ++j)
; #pragma unroll
;           for (int g = 0; g < 16; ++g) Cs[(i * 32 + crow(g, h)) * CSW + wn * 64 + j * 32 + r] = acc[i][j][g];
	v_mfma_f32_32x32x16_bf16 v[114:129], v[218:221], v[234:237], v[114:129]
	v_mfma_f32_32x32x16_bf16 v[98:113], v[218:221], v[202:205], v[98:113]
	v_mfma_f32_32x32x16_bf16 v[82:97], v[222:225], v[234:237], v[82:97]
	v_mfma_f32_32x32x16_bf16 v[66:81], v[222:225], v[202:205], v[66:81]
	v_mfma_f32_32x32x16_bf16 v[50:65], v[226:229], v[234:237], v[50:65]
	v_mfma_f32_32x32x16_bf16 v[34:49], v[226:229], v[202:205], v[34:49]
	v_mfma_f32_32x32x16_bf16 v[18:33], v[230:233], v[234:237], v[18:33]
	v_mfma_f32_32x32x16_bf16 v[2:17], v[230:233], v[202:205], v[2:17]
	v_mov_b32_e32 v190, 0x10c20
	v_mov_b32_e32 v191, 0x11040
	v_mov_b32_e32 v192, 0x11460
	v_mov_b32_e32 v193, 0x12900
	v_mov_b32_e32 v194, 0x12d20
	v_mov_b32_e32 v195, 0x13140
	v_mov_b32_e32 v196, 0x13560
	v_mov_b32_e32 v197, 0x14a00
	v_mov_b32_e32 v198, 0x14e20
	v_mov_b32_e32 v199, 0x15240
	v_mov_b32_e32 v200, 0x15660
	v_mov_b32_e32 v201, 0x16b00
	v_mov_b32_e32 v202, 0x16f20
	v_mov_b32_e32 v203, 0x17340
	v_mov_b32_e32 v204, 0x17760
	v_mov_b32_e32 v205, 0x18c00
	v_mov_b32_e32 v206, 0x19020
	v_mov_b32_e32 v207, 0x19440
	v_mov_b32_e32 v208, 0x10800
	v_lshrrev_b32_e32 v218, 8, v165
	v_bfe_u32 v219, v165, 5, 1
	v_and_b32_e32 v220, 31, v165
	v_bfe_u32 v221, v165, 6, 2
	s_mov_b32 s10, 0
	s_movk_i32 s4, 0x1080
	v_mov_b32_e32 v157, 0x1da60
	v_mad_u32_u24 v154, v219, s4, v245
	v_mad_u32_u24 v155, v219, s4, v246
	v_mad_u32_u24 v156, v219, s4, v247
	v_mad_u32_u24 v157, v219, s4, v157
	v_mov_b32_e32 v158, 0x1ef00
	v_mov_b32_e32 v159, 0x1f320
	v_mov_b32_e32 v160, 0x1f740
	v_mad_u32_u24 v158, v219, s4, v158
	v_mad_u32_u24 v159, v219, s4, v159
	v_mad_u32_u24 v160, v219, s4, v160
	v_lshlrev_b32_e32 v0, 8, v221
	v_mov_b32_e32 v166, 0x1fb60
	v_lshl_or_b32 v161, v220, 2, v0
	v_mad_u32_u24 v166, v219, s4, v166
	v_mad_u32_u24 v0, v219, s4, v161
	v_add_u32_e32 v154, v161, v154
	v_add_u32_e32 v155, v161, v155
	v_add_u32_e32 v156, v161, v156
	v_add_u32_e32 v157, v161, v157
	v_mad_u32_u24 v130, v219, s4, v208
	v_mad_u32_u24 v131, v219, s4, v190
	v_mad_u32_u24 v132, v219, s4, v191
	v_mad_u32_u24 v133, v219, s4, v192
	v_add_u32_e32 v130, v161, v130
	v_add_u32_e32 v131, v161, v131
	v_add_u32_e32 v132, v161, v132
	v_add_u32_e32 v133, v161, v133
	v_add_u32_e32 v158, v161, v158
	v_add_u32_e32 v159, v161, v159
	v_add_u32_e32 v160, v161, v160
	v_mad_u32_u24 v134, v219, s4, v193
	v_mad_u32_u24 v135, v219, s4, v194
	v_mad_u32_u24 v136, v219, s4, v195
	v_mad_u32_u24 v137, v219, s4, v196
	v_add_u32_e32 v134, v161, v134
	v_add_u32_e32 v135, v161, v135
	v_add_u32_e32 v136, v161, v136
	v_add_u32_e32 v137, v161, v137
	v_mad_u32_u24 v138, v219, s4, v197
	v_mad_u32_u24 v139, v219, s4, v198
	v_mad_u32_u24 v140, v219, s4, v199
	v_mad_u32_u24 v141, v219, s4, v200
	v_add_u32_e32 v138, v161, v138
	v_add_u32_e32 v139, v161, v139
	v_add_u32_e32 v140, v161, v140
	v_mad_u32_u24 v146, v219, s4, v205
	v_mad_u32_u24 v147, v219, s4, v206
	v_mad_u32_u24 v148, v219, s4, v207
	v_mad_u32_u24 v149, v219, s4, v240
	v_add_u32_e32 v141, v161, v141
	v_add_u32_e32 v146, v161, v146
	v_add_u32_e32 v147, v161, v147
	v_mad_u32_u24 v142, v219, s4, v201
	v_mad_u32_u24 v143, v219, s4, v202
	v_mad_u32_u24 v144, v219, s4, v203
	v_mad_u32_u24 v145, v219, s4, v204
	v_mad_u32_u24 v150, v219, s4, v241
	v_mad_u32_u24 v151, v219, s4, v242
	v_mad_u32_u24 v152, v219, s4, v243
	v_mad_u32_u24 v153, v219, s4, v244
	s_mov_b64 s[4:5], -1
	v_add_u32_e32 v142, v161, v142
	v_add_u32_e32 v143, v161, v143
	v_add_u32_e32 v144, v161, v144
	v_add_u32_e32 v145, v161, v145
	v_add_u32_e32 v148, v161, v148
	v_add_u32_e32 v149, v161, v149
	v_add_u32_e32 v150, v161, v150
	v_add_u32_e32 v151, v161, v151
	v_add_u32_e32 v152, v161, v152
	v_add_u32_e32 v153, v161, v153
	v_add_u32_e32 v161, v161, v166
	s_branch .LBB0_837

; #define G5_LOAD(k0)                                                                 \
;   {                                                                                 \
;     _Pragma("unroll") for (int i_ = 0; i_ < 4; ++i_) ra[i_] = ldg16(Ap + (size_t)(i_ * 64) * lda + (k0)); \
;     _Pragma("unroll") for (int i_ = 0; i_ < 4; ++i_) rb[i_] = ldg16(Bp + (size_t)(i_ * 64) * ldb + (k0)); \
;   }
; #define G5_STORE(s)                                                                 \
;   {                                                                                 \
;     _Pragma("unroll") for (int i_ = 0; i_ < 4; ++i_) *(u32x4*)(Sw + (s) * STG + i_ * 64 * GS) = ra[i_]; \
;     _Pragma("unroll") for (int i_ = 0; i_ < 4; ++i_) *(u32x4*)(Sw + (s) * STG + 256 * GS + i_ * 64 * GS) = rb[i_]; \
;   }
; template <typename Epi>
; DI void gemm_tile512(const u16* __restrict__ A, int lda, const u16* __restrict__ Bt, int ldb, int K, char* lds_all, Epi epi) {
;     ...
;   const int lrow = tid >> 3, lcol = (tid & 7) * 8;
;   const u16* Ap = A + (size_t)lrow * lda + lcol;
;   const u16* Bp = Bt + (size_t)lrow * ldb + lcol;
;   u16* Sw = S0 + lrow * GS + lcol;
;   u32x4 ra[4], rb[4];
;     ...
;   const int nk = K >> 6;
;   __syncthreads();
;   G5_LOAD(0);
;   G5_STORE(0);
;   G5_LOAD(64);
;   __syncthreads();
;   for (int kt = 0; kt + 2 < nk; ++kt) {
;     const int cur = kt & 1;
;     G5_COMPUTE(cur);
;     G5_STORE(cur ^ 1);
;     G5_LOAD((kt + 2) << 6);
;     __syncthreads();
;   }
.LBB0_852:
	s_lshl_b32 s15, s11, 9
	s_lshl_b32 s11, s23, 8
	s_and_b32 s11, s11, 0x100
	s_lshl_b32 s26, s10, 10
	s_lshl_b32 s10, s23, 7
	s_or_b32 s24, s11, s15
	s_sub_i32 s10, s10, s26
	s_and_b32 s25, s10, 0xffffff00
	s_mul_i32 s10, s24, 0x2100
	s_mul_hi_i32 s11, s24, 0x2100
	s_add_u32 s10, s50, s10
	s_addc_u32 s11, s51, s11
	s_mul_i32 s12, s25, 0x2100
	s_mul_hi_i32 s13, s25, 0x2100
	s_add_u32 s12, s30, s12
	s_addc_u32 s13, s31, s13
	s_mov_b64 s[98:99], s[10:11]
	s_mov_b64 s[100:101], s[12:13]
	v_lshrrev_b32_e32 v239, 3, v165
	v_and_b32_e32 v0, 7, v165
	v_mul_u32_u24_e32 v206, 0x2100, v239
	v_lshl_add_u32 v206, v0, 4, v206
	v_add_u32_e32 v207, 0x84000, v206
	v_add_u32_e32 v208, 0x108000, v206
	v_add_u32_e32 v238, 0x18c000, v206
	v_mul_u32_u24_e32 v180, 0x90, v239
	v_lshl_add_u32 v180, v0, 4, v180
	global_load_dwordx4 v[2:5], v206, s[98:99]
	global_load_dwordx4 v[6:9], v207, s[98:99]
	global_load_dwordx4 v[10:13], v208, s[98:99]
	global_load_dwordx4 v[14:17], v238, s[98:99]
	global_load_dwordx4 v[18:21], v206, s[100:101]
	global_load_dwordx4 v[22:25], v207, s[100:101]
	global_load_dwordx4 v[26:29], v208, s[100:101]
	global_load_dwordx4 v[30:33], v238, s[100:101]
	global_load_dwordx4 v[130:133], v206, s[98:99] offset:128
	global_load_dwordx4 v[134:137], v207, s[98:99] offset:128
	global_load_dwordx4 v[138:141], v208, s[98:99] offset:128
	global_load_dwordx4 v[142:145], v238, s[98:99] offset:128
	global_load_dwordx4 v[146:149], v206, s[100:101] offset:128
	global_load_dwordx4 v[150:153], v207, s[100:101] offset:128
	global_load_dwordx4 v[154:157], v208, s[100:101] offset:128
	global_load_dwordx4 v[158:161], v238, s[100:101] offset:128
	s_add_u32 s98, s98, 0x100
	s_addc_u32 s99, s99, 0
	s_add_u32 s100, s100, 0x100
	s_addc_u32 s101, s101, 0
	v_and_b32_e32 v239, 31, v165
	v_bfe_u32 v0, v165, 5, 1
	v_lshrrev_b32_e32 v179, 8, v165
	v_lshl_or_b32 v178, v179, 7, v239
	v_mul_u32_u24_e32 v178, 0x90, v178
	v_lshl_add_u32 v178, v0, 4, v178
	v_bfe_u32 v179, v165, 6, 2
	v_lshl_or_b32 v179, v179, 6, v239
	v_mul_u32_u24_e32 v179, 0x90, v179
	v_lshl_add_u32 v179, v0, 4, v179
	s_mov_b32 s14, 0x12000
	s_mov_b32 s15, 61
	s_barrier
	s_waitcnt vmcnt(15)
	ds_write_b128 v180, v[2:5]
	s_waitcnt vmcnt(14)
	ds_write_b128 v180, v[6:9] offset:9216
	s_waitcnt vmcnt(13)
	ds_write_b128 v180, v[10:13] offset:18432
	s_waitcnt vmcnt(12)
	ds_write_b128 v180, v[14:17] offset:27648
	s_waitcnt vmcnt(11)
	ds_write_b128 v180, v[18:21] offset:36864
	s_waitcnt vmcnt(10)
	ds_write_b128 v180, v[22:25] offset:46080
	s_waitcnt vmcnt(9)
	ds_write_b128 v180, v[26:29] offset:55296
	s_waitcnt vmcnt(8)
	ds_write_b128 v180, v[30:33] offset:64512
	v_add_u32_e32 v180, 0x12000, v180
	s_waitcnt lgkmcnt(0)
	s_barrier
	ds_read_b128 v[194:197], v179 offset:36864
	ds_read_b128 v[166:169], v178
	ds_read_b128 v[198:201], v179 offset:41472
	ds_read_b128 v[170:173], v178 offset:4608
	ds_read_b128 v[174:177], v178 offset:9216
	ds_read_b128 v[190:193], v178 offset:13824
	s_waitcnt lgkmcnt(4)
	v_mfma_f32_32x32x16_bf16 v[114:129], v[166:169], v[194:197], 0
	ds_read_b128 v[234:237], v179 offset:36896
	s_waitcnt lgkmcnt(4)
	v_mfma_f32_32x32x16_bf16 v[98:113], v[166:169], v[198:201], 0
	ds_read_b128 v[218:221], v178 offset:32
	s_waitcnt vmcnt(7)
	ds_write_b128 v180, v[130:133]
	global_load_dwordx4 v[130:133], v206, s[98:99]
	s_waitcnt lgkmcnt(5)
	v_mfma_f32_32x32x16_bf16 v[82:97], v[170:173], v[194:197], 0
	ds_read_b128 v[202:205], v179 offset:41504
	v_mfma_f32_32x32x16_bf16 v[66:81], v[170:173], v[198:201], 0
	ds_read_b128 v[222:225], v178 offset:4640
	s_waitcnt vmcnt(7)
	ds_write_b128 v180, v[134:137] offset:9216
	global_load_dwordx4 v[134:137], v207, s[98:99]
	s_waitcnt lgkmcnt(7)
	v_mfma_f32_32x32x16_bf16 v[50:65], v[174:177], v[194:197], 0
	ds_read_b128 v[226:229], v178 offset:9248
	v_mfma_f32_32x32x16_bf16 v[34:49], v[174:177], v[198:201], 0
	ds_read_b128 v[230:233], v178 offset:13856
	s_waitcnt vmcnt(7)
	ds_write_b128 v180, v[138:141] offset:18432
	global_load_dwordx4 v[138:141], v208, s[98:99]
	s_waitcnt lgkmcnt(9)
	v_mfma_f32_32x32x16_bf16 v[18:33], v[190:193], v[194:197], 0
	v_mfma_f32_32x32x16_bf16 v[2:17], v[190:193], v[198:201], 0
	s_waitcnt vmcnt(7)
	ds_write_b128 v180, v[142:145] offset:27648
	global_load_dwordx4 v[142:145], v238, s[98:99]
	s_waitcnt lgkmcnt(8)
	v_mfma_f32_32x32x16_bf16 v[114:129], v[218:221], v[234:237], v[114:129]
	ds_read_b128 v[194:197], v179 offset:36928
	s_waitcnt lgkmcnt(7)
	v_mfma_f32_32x32x16_bf16 v[98:113], v[218:221], v[202:205], v[98:113]
	ds_read_b128 v[166:169], v178 offset:64
	s_waitcnt vmcnt(7)
	ds_write_b128 v180, v[146:149] offset:36864
	global_load_dwordx4 v[146:149], v206, s[100:101]
	s_waitcnt lgkmcnt(8)
	v_mfma_f32_32x32x16_bf16 v[82:97], v[222:225], v[234:237], v[82:97]
	ds_read_b128 v[198:201], v179 offset:41536
	v_mfma_f32_32x32x16_bf16 v[66:81], v[222:225], v[202:205], v[66:81]
	ds_read_b128 v[170:173], v178 offset:4672
	s_waitcnt vmcnt(7)
	ds_write_b128 v180, v[150:153] offset:46080
	global_load_dwordx4 v[150:153], v207, s[100:101]
	s_waitcnt lgkmcnt(9)
	v_mfma_f32_32x32x16_bf16 v[50:65], v[226:229], v[234:237], v[50:65]
	ds_read_b128 v[174:177], v178 offset:9280
	v_mfma_f32_32x32x16_bf16 v[34:49], v[226:229], v[202:205], v[34:49]
	ds_read_b128 v[190:193], v178 offset:13888
	s_waitcnt vmcnt(7)
	ds_write_b128 v180, v[154:157] offset:55296
	global_load_dwordx4 v[154:157], v208, s[100:101]
	s_waitcnt lgkmcnt(11)
	v_mfma_f32_32x32x16_bf16 v[18:33], v[230:233], v[234:237], v[18:33]
	v_mfma_f32_32x32x16_bf16 v[2:17], v[230:233], v[202:205], v[2:17]
	s_waitcnt vmcnt(7)
	ds_write_b128 v180, v[158:161] offset:64512
	global_load_dwordx4 v[158:161], v238, s[100:101]
	v_subrev_u32_e32 v180, s14, v180
	s_waitcnt lgkmcnt(8)
	v_mfma_f32_32x32x16_bf16 v[114:129], v[166:169], v[194:197], v[114:129]
	ds_read_b128 v[234:237], v179 offset:36960
	s_waitcnt lgkmcnt(7)
	v_mfma_f32_32x32x16_bf16 v[98:113], v[166:169], v[198:201], v[98:113]
	ds_read_b128 v[218:221], v178 offset:96
	s_waitcnt lgkmcnt(7)
	v_mfma_f32_32x32x16_bf16 v[82:97], v[170:173], v[194:197], v[82:97]
	ds_read_b128 v[202:205], v179 offset:41568
	v_mfma_f32_32x32x16_bf16 v[66:81], v[170:173], v[198:201], v[66:81]
	ds_read_b128 v[222:225], v178 offset:4704
	s_waitcnt lgkmcnt(7)
	v_mfma_f32_32x32x16_bf16 v[50:65], v[174:177], v[194:197], v[50:65]
	ds_read_b128 v[226:229], v178 offset:9312
	v_mfma_f32_32x32x16_bf16 v[34:49], v[174:177], v[198:201], v[34:49]
	ds_read_b128 v[230:233], v178 offset:13920
	v_add_u32_e32 v178, s14, v178
	v_add_u32_e32 v179, s14, v179
	s_waitcnt lgkmcnt(8)
	v_mfma_f32_32x32x16_bf16 v[18:33], v[190:193], v[194:197], v[18:33]
	v_mfma_f32_32x32x16_bf16 v[2:17], v[190:193], v[198:201], v[2:17]
	s_sub_u32 s14, 0, s14
	s_add_u32 s98, s98, 0x80
	s_addc_u32 s99, s99, 0
	s_add_u32 s100, s100, 0x80
	s_addc_u32 s101, s101, 0
	s_waitcnt lgkmcnt(0)
; #define G5_LOAD(k0)                                                                 \
;   {                                                                                 \
;     _Pragma("unroll") for (int i_ = 0; i_ < 4; ++i_) ra[i_] = ldg16(Ap + (size_t)(i_ * 64) * lda + (k0)); \
;     _Pragma("unroll") for (int i_ = 0; i_ < 4; ++i_) rb[i_] = ldg16(Bp + (size_t)(i_ * 64) * ldb + (k0)); \
;   }
; #define G5_STORE(s)                                                                 \
;   {                                                                                 \
;     _Pragma("unroll") for (int i_ = 0; i_ < 4; ++i_) *(u32x4*)(Sw + (s) * STG + i_ * 64 * GS) = ra[i_]; \
;     _Pragma("unroll") for (int i_ = 0; i_ < 4; ++i_) *(u32x4*)(Sw + (s) * STG + 256 * GS + i_ * 64 * GS) = rb[i_]; \
;   }
; template <typename Epi>
; DI void gemm_tile512(const u16* __restrict__ A, int lda, const u16* __restrict__ Bt, int ldb, int K, char* lds_all, Epi epi) {
;     ...
;   const int nk = K >> 6;
;   __syncthreads();
;   G5_LOAD(0);
;   G5_STORE(0);
;   G5_LOAD(64);
;   __syncthreads();
;   for (int kt = 0; kt + 2 < nk; ++kt) {
;     const int cur = kt & 1;
;     G5_COMPUTE(cur);
;     G5_STORE(cur ^ 1);
;     G5_LOAD((kt + 2) << 6);
;     __syncthreads();
;   }
.Lgemm_loop_m3_0:
	s_barrier
	ds_read_b128 v[194:197], v179 offset:36864
	ds_read_b128 v[166:169], v178
	v_mfma_f32_32x32x16_bf16 v[114:129], v[218:221], v[234:237], v[114:129]
	ds_read_b128 v[198:201], v179 offset:41472
	v_mfma_f32_32x32x16_bf16 v[98:113], v[218:221], v[202:205], v[98:113]
	ds_read_b128 v[170:173], v178 offset:4608
	v_mfma_f32_32x32x16_bf16 v[82:97], v[222:225], v[234:237], v[82:97]
	ds_read_b128 v[174:177], v178 offset:9216
	v_mfma_f32_32x32x16_bf16 v[66:81], v[222:225], v[202:205], v[66:81]
	ds_read_b128 v[190:193], v178 offset:13824
	v_mfma_f32_32x32x16_bf16 v[50:65], v[226:229], v[234:237], v[50:65]
	v_mfma_f32_32x32x16_bf16 v[34:49], v[226:229], v[202:205], v[34:49]
	v_mfma_f32_32x32x16_bf16 v[18:33], v[230:233], v[234:237], v[18:33]
	v_mfma_f32_32x32x16_bf16 v[2:17], v[230:233], v[202:205], v[2:17]
	s_waitcnt lgkmcnt(4)
	v_mfma_f32_32x32x16_bf16 v[114:129], v[166:169], v[194:197], v[114:129]
	ds_read_b128 v[234:237], v179 offset:36896
	s_waitcnt lgkmcnt(4)
	v_mfma_f32_32x32x16_bf16 v[98:113], v[166:169], v[198:201], v[98:113]
	ds_read_b128 v[218:221], v178 offset:32
	s_waitcnt vmcnt(7)
	ds_write_b128 v180, v[130:133]
	global_load_dwordx4 v[130:133], v206, s[98:99]
	s_waitcnt lgkmcnt(5)
	v_mfma_f32_32x32x16_bf16 v[82:97], v[170:173], v[194:197], v[82:97]
	ds_read_b128 v[202:205], v179 offset:41504
	v_mfma_f32_32x32x16_bf16 v[66:81], v[170:173], v[198:201], v[66:81]
	ds_read_b128 v[222:225], v178 offset:4640
	s_waitcnt vmcnt(7)
	ds_write_b128 v180, v[134:137] offset:9216
	global_load_dwordx4 v[134:137], v207, s[98:99]
	s_waitcnt lgkmcnt(7)
	v_mfma_f32_32x32x16_bf16 v[50:65], v[174:177], v[194:197], v[50:65]
	ds_read_b128 v[226:229], v178 offset:9248
	v_mfma_f32_32x32x16_bf16 v[34:49], v[174:177], v[198:201], v[34:49]
	ds_read_b128 v[230:233], v178 offset:13856
	s_waitcnt vmcnt(7)
	ds_write_b128 v180, v[138:141] offset:18432
	global_load_dwordx4 v[138:141], v208, s[98:99]
	s_waitcnt lgkmcnt(9)
	v_mfma_f32_32x32x16_bf16 v[18:33], v[190:193], v[194:197], v[18:33]
	v_mfma_f32_32x32x16_bf16 v[2:17], v[190:193], v[198:201], v[2:17]
	s_waitcnt vmcnt(7)
	ds_write_b128 v180, v[142:145] offset:27648
	global_load_dwordx4 v[142:145], v238, s[98:99]
	s_waitcnt lgkmcnt(8)
	v_mfma_f32_32x32x16_bf16 v[114:129], v[218:221], v[234:237], v[114:129]
	ds_read_b128 v[194:197], v179 offset:36928
	s_waitcnt lgkmcnt(7)
	v_mfma_f32_32x32x16_bf16 v[98:113], v[218:221], v[202:205], v[98:113]
	ds_read_b128 v[166:169], v178 offset:64
	s_waitcnt vmcnt(7)
	ds_write_b128 v180, v[146:149] offset:36864
	global_load_dwordx4 v[146:149], v206, s[100:101]
	s_waitcnt lgkmcnt(8)
	v_mfma_f32_32x32x16_bf16 v[82:97], v[222:225], v[234:237], v[82:97]
	ds_read_b128 v[198:201], v179 offset:41536
	v_mfma_f32_32x32x16_bf16 v[66:81], v[222:225], v[202:205], v[66:81]
	ds_read_b128 v[170:173], v178 offset:4672
	s_waitcnt vmcnt(7)
	ds_write_b128 v180, v[150:153] offset:46080
	global_load_dwordx4 v[150:153], v207, s[100:101]
	s_waitcnt lgkmcnt(9)
	v_mfma_f32_32x32x16_bf16 v[50:65], v[226:229], v[234:237], v[50:65]
	ds_read_b128 v[174:177], v178 offset:9280
	v_mfma_f32_32x32x16_bf16 v[34:49], v[226:229], v[202:205], v[34:49]
	ds_read_b128 v[190:193], v178 offset:13888
	s_waitcnt vmcnt(7)
	ds_write_b128 v180, v[154:157] offset:55296
	global_load_dwordx4 v[154:157], v208, s[100:101]
	s_waitcnt lgkmcnt(11)
	v_mfma_f32_32x32x16_bf16 v[18:33], v[230:233], v[234:237], v[18:33]
	v_mfma_f32_32x32x16_bf16 v[2:17], v[230:233], v[202:205], v[2:17]
	s_waitcnt vmcnt(7)
	ds_write_b128 v180, v[158:161] offset:64512
	global_load_dwordx4 v[158:161], v238, s[100:101]
	v_subrev_u32_e32 v180, s14, v180
	s_waitcnt lgkmcnt(8)
	v_mfma_f32_32x32x16_bf16 v[114:129], v[166:169], v[194:197], v[114:129]
	ds_read_b128 v[234:237], v179 offset:36960
	s_waitcnt lgkmcnt(7)
	v_mfma_f32_32x32x16_bf16 v[98:113], v[166:169], v[198:201], v[98:113]
	ds_read_b128 v[218:221], v178 offset:96
	s_waitcnt lgkmcnt(7)
	v_mfma_f32_32x32x16_bf16 v[82:97], v[170:173], v[194:197], v[82:97]
	ds_read_b128 v[202:205], v179 offset:41568
	v_mfma_f32_32x32x16_bf16 v[66:81], v[170:173], v[198:201], v[66:81]
	ds_read_b128 v[222:225], v178 offset:4704
	s_waitcnt lgkmcnt(7)
	v_mfma_f32_32x32x16_bf16 v[50:65], v[174:177], v[194:197], v[50:65]
	ds_read_b128 v[226:229], v178 offset:9312
	v_mfma_f32_32x32x16_bf16 v[34:49], v[174:177], v[198:201], v[34:49]
	ds_read_b128 v[230:233], v178 offset:13920
	v_add_u32_e32 v178, s14, v178
	v_add_u32_e32 v179, s14, v179
	s_waitcnt lgkmcnt(8)
	v_mfma_f32_32x32x16_bf16 v[18:33], v[190:193], v[194:197], v[18:33]
	v_mfma_f32_32x32x16_bf16 v[2:17], v[190:193], v[198:201], v[2:17]
	s_sub_u32 s14, 0, s14
	s_add_u32 s98, s98, 0x80
	s_addc_u32 s99, s99, 0
	s_add_u32 s100, s100, 0x80
	s_addc_u32 s101, s101, 0
	s_waitcnt lgkmcnt(0)
	s_sub_u32 s15, s15, 1
	s_cmp_lg_u32 s15, 0
	s_cbranch_scc1 .Lgemm_loop_m3_0
	s_barrier
; #define G5_STORE(s)                                                                 \
;   {                                                                                 \
;     _Pragma("unroll") for (int i_ = 0; i_ < 4; ++i_) *(u32x4*)(Sw + (s) * STG + i_ * 64 * GS) = ra[i_]; \
;     _Pragma("unroll") for (int i_ = 0; i_ < 4; ++i_) *(u32x4*)(Sw + (s) * STG + 256 * GS + i_ * 64 * GS) = rb[i_]; \
;   }
; template <typename Epi>
; DI void gemm_tile512(const u16* __restrict__ A, int lda, const u16* __restrict__ Bt, int ldb, int K, char* lds_all, Epi epi) {
;     ...
;   {
;     const int cur = (nk - 2) & 1;
;     G5_COMPUTE(cur);
;     G5_STORE(cur ^ 1);
;     __syncthreads();
	ds_read_b128 v[194:197], v179 offset:36864
	ds_read_b128 v[166:169], v178
	v_mfma_f32_32x32x16_bf16 v[114:129], v[218:221], v[234:237], v[114:129]
	ds_read_b128 v[198:201], v179 offset:41472
	v_mfma_f32_32x32x16_bf16 v[98:113], v[218:221], v[202:205], v[98:113]
	ds_read_b128 v[170:173], v178 offset:4608
	v_mfma_f32_32x32x16_bf16 v[82:97], v[222:225], v[234:237], v[82:97]
	ds_read_b128 v[174:177], v178 offset:9216
	v_mfma_f32_32x32x16_bf16 v[66:81], v[222:225], v[202:205], v[66:81]
	ds_read_b128 v[190:193], v178 offset:13824
	v_mfma_f32_32x32x16_bf16 v[50:65], v[226:229], v[234:237], v[50:65]
	v_mfma_f32_32x32x16_bf16 v[34:49], v[226:229], v[202:205], v[34:49]
	v_mfma_f32_32x32x16_bf16 v[18:33], v[230:233], v[234:237], v[18:33]
	v_mfma_f32_32x32x16_bf16 v[2:17], v[230:233], v[202:205], v[2:17]
	s_waitcnt lgkmcnt(4)
	v_mfma_f32_32x32x16_bf16 v[114:129], v[166:169], v[194:197], v[114:129]
	ds_read_b128 v[234:237], v179 offset:36896
	s_waitcnt lgkmcnt(4)
	v_mfma_f32_32x32x16_bf16 v[98:113], v[166:169], v[198:201], v[98:113]
	ds_read_b128 v[218:221], v178 offset:32
	s_waitcnt vmcnt(7)
	ds_write_b128 v180, v[130:133]
	s_waitcnt lgkmcnt(5)
	v_mfma_f32_32x32x16_bf16 v[82:97], v[170:173], v[194:197], v[82:97]
	ds_read_b128 v[202:205], v179 offset:41504
	v_mfma_f32_32x32x16_bf16 v[66:81], v[170:173], v[198:201], v[66:81]
	ds_read_b128 v[222:225], v178 offset:4640
	s_waitcnt vmcnt(6)
	ds_write_b128 v180, v[134:137] offset:9216
	s_waitcnt lgkmcnt(7)
	v_mfma_f32_32x32x16_bf16 v[50:65], v[174:177], v[194:197], v[50:65]
	ds_read_b128 v[226:229], v178 offset:9248
	v_mfma_f32_32x32x16_bf16 v[34:49], v[174:177], v[198:201], v[34:49]
	ds_read_b128 v[230:233], v178 offset:13856
	s_waitcnt vmcnt(5)
	ds_write_b128 v180, v[138:141] offset:18432
	s_waitcnt lgkmcnt(9)
	v_mfma_f32_32x32x16_bf16 v[18:33], v[190:193], v[194:197], v[18:33]
	v_mfma_f32_32x32x16_bf16 v[2:17], v[190:193], v[198:201], v[2:17]
	s_waitcnt vmcnt(4)
	ds_write_b128 v180, v[142:145] offset:27648
	s_waitcnt lgkmcnt(8)
	v_mfma_f32_32x32x16_bf16 v[114:129], v[218:221], v[234:237], v[114:129]
	ds_read_b128 v[194:197], v179 offset:36928
	s_waitcnt lgkmcnt(7)
	v_mfma_f32_32x32x16_bf16 v[98:113], v[218:221], v[202:205], v[98:113]
	ds_read_b128 v[166:169], v178 offset:64
	s_waitcnt vmcnt(3)
	ds_write_b128 v180, v[146:149] offset:36864
	s_waitcnt lgkmcnt(8)
	v_mfma_f32_32x32x16_bf16 v[82:97], v[222:225], v[234:237], v[82:97]
	ds_read_b128 v[198:201], v179 offset:41536
	v_mfma_f32_32x32x16_bf16 v[66:81], v[222:225], v[202:205], v[66:81]
	ds_read_b128 v[170:173], v178 offset:4672
	s_waitcnt vmcnt(2)
	ds_write_b128 v180, v[150:153] offset:46080
	s_waitcnt lgkmcnt(9)
	v_mfma_f32_32x32x16_bf16 v[50:65], v[226:229], v[234:237], v[50:65]
	ds_read_b128 v[174:177], v178 offset:9280
	v_mfma_f32_32x32x16_bf16 v[34:49], v[226:229], v[202:205], v[34:49]
	ds_read_b128 v[190:193], v178 offset:13888
	s_waitcnt vmcnt(1)
	ds_write_b128 v180, v[154:157] offset:55296
	s_waitcnt lgkmcnt(11)
	v_mfma_f32_32x32x16_bf16 v[18:33], v[230:233], v[234:237], v[18:33]
	v_mfma_f32_32x32x16_bf16 v[2:17], v[230:233], v[202:205], v[2:17]
	s_waitcnt vmcnt(0)
	ds_write_b128 v180, v[158:161] offset:64512
	v_subrev_u32_e32 v180, s14, v180
	s_waitcnt lgkmcnt(8)
	v_mfma_f32_32x32x16_bf16 v[114:129], v[166:169], v[194:197], v[114:129]
	ds_read_b128 v[234:237], v179 offset:36960
	s_waitcnt lgkmcnt(7)
	v_mfma_f32_32x32x16_bf16 v[98:113], v[166:169], v[198:201], v[98:113]
	ds_read_b128 v[218:221], v178 offset:96
	s_waitcnt lgkmcnt(7)
	v_mfma_f32_32x32x16_bf16 v[82:97], v[170:173], v[194:197], v[82:97]
	ds_read_b128 v[202:205], v179 offset:41568
	v_mfma_f32_32x32x16_bf16 v[66:81], v[170:173], v[198:201], v[66:81]
	ds_read_b128 v[222:225], v178 offset:4704
	s_waitcnt lgkmcnt(7)
	v_mfma_f32_32x32x16_bf16 v[50:65], v[174:177], v[194:197], v[50:65]
	ds_read_b128 v[226:229], v178 offset:9312
	v_mfma_f32_32x32x16_bf16 v[34:49], v[174:177], v[198:201], v[34:49]
	ds_read_b128 v[230:233], v178 offset:13920
	v_add_u32_e32 v178, s14, v178
	v_add_u32_e32 v179, s14, v179
	s_waitcnt lgkmcnt(8)
	v_mfma_f32_32x32x16_bf16 v[18:33], v[190:193], v[194:197], v[18:33]
	v_mfma_f32_32x32x16_bf16 v[2:17], v[190:193], v[198:201], v[2:17]
	s_sub_u32 s14, 0, s14
	s_waitcnt lgkmcnt(0)
	s_barrier
; #define G5_STORE(s)                                                                 \
;   {                                                                                 \
;     _Pragma("unroll") for (int i_ = 0; i_ < 4; ++i_) *(u32x4*)(Sw + (s) * STG + i_ * 64 * GS) = ra[i_]; \
;     _Pragma("unroll") for (int i_ = 0; i_ < 4; ++i_) *(u32x4*)(Sw + (s) * STG + 256 * GS + i_ * 64 * GS) = rb[i_]; \
;   }
; template <typename Epi>
; DI void gemm_tile512(const u16* __restrict__ A, int lda, const u16* __restrict__ Bt, int ldb, int K, char* lds_all, Epi epi) {
;     ...
;   {
;     const int cur = (nk - 2) & 1;
;     G5_COMPUTE(cur);
;     G5_STORE(cur ^ 1);
;     __syncthreads();
;     G5_COMPUTE(cur ^ 1);
;   }
	ds_read_b128 v[194:197], v179 offset:36864
	ds_read_b128 v[166:169], v178
	v_mfma_f32_32x32x16_bf16 v[114:129], v[218:221], v[234:237], v[114:129]
	ds_read_b128 v[198:201], v179 offset:41472
	v_mfma_f32_32x32x16_bf16 v[98:113], v[218:221], v[202:205], v[98:113]
	ds_read_b128 v[170:173], v178 offset:4608
	v_mfma_f32_32x32x16_bf16 v[82:97], v[222:225], v[234:237], v[82:97]
	ds_read_b128 v[174:177], v178 offset:9216
	v_mfma_f32_32x32x16_bf16 v[66:81], v[222:225], v[202:205], v[66:81]
	ds_read_b128 v[190:193], v178 offset:13824
	v_mfma_f32_32x32x16_bf16 v[50:65], v[226:229], v[234:237], v[50:65]
	v_mfma_f32_32x32x16_bf16 v[34:49], v[226:229], v[202:205], v[34:49]
	v_mfma_f32_32x32x16_bf16 v[18:33], v[230:233], v[234:237], v[18:33]
	v_mfma_f32_32x32x16_bf16 v[2:17], v[230:233], v[202:205], v[2:17]
	s_waitcnt lgkmcnt(4)
	v_mfma_f32_32x32x16_bf16 v[114:129], v[166:169], v[194:197], v[114:129]
	ds_read_b128 v[234:237], v179 offset:36896
	s_waitcnt lgkmcnt(4)
	v_mfma_f32_32x32x16_bf16 v[98:113], v[166:169], v[198:201], v[98:113]
	ds_read_b128 v[218:221], v178 offset:32
	s_waitcnt lgkmcnt(4)
	v_mfma_f32_32x32x16_bf16 v[82:97], v[170:173], v[194:197], v[82:97]
	ds_read_b128 v[202:205], v179 offset:41504
	v_mfma_f32_32x32x16_bf16 v[66:81], v[170:173], v[198:201], v[66:81]
	ds_read_b128 v[222:225], v178 offset:4640
	s_waitcnt lgkmcnt(5)
	v_mfma_f32_32x32x16_bf16 v[50:65], v[174:177], v[194:197], v[50:65]
	ds_read_b128 v[226:229], v178 offset:9248
	v_mfma_f32_32x32x16_bf16 v[34:49], v[174:177], v[198:201], v[34:49]
	ds_read_b128 v[230:233], v178 offset:13856
	s_waitcnt lgkmcnt(6)
	v_mfma_f32_32x32x16_bf16 v[18:33], v[190:193], v[194:197], v[18:33]
	v_mfma_f32_32x32x16_bf16 v[2:17], v[190:193], v[198:201], v[2:17]
	s_waitcnt lgkmcnt(4)
	v_mfma_f32_32x32x16_bf16 v[114:129], v[218:221], v[234:237], v[114:129]
	ds_read_b128 v[194:197], v179 offset:36928
	s_waitcnt lgkmcnt(4)
	v_mfma_f32_32x32x16_bf16 v[98:113], v[218:221], v[202:205], v[98:113]
	ds_read_b128 v[166:169], v178 offset:64
	s_waitcnt lgkmcnt(4)
	v_mfma_f32_32x32x16_bf16 v[82:97], v[222:225], v[234:237], v[82:97]
	ds_read_b128 v[198:201], v179 offset:41536
	v_mfma_f32_32x32x16_bf16 v[66:81], v[222:225], v[202:205], v[66:81]
	ds_read_b128 v[170:173], v178 offset:4672
	s_waitcnt lgkmcnt(5)
	v_mfma_f32_32x32x16_bf16 v[50:65], v[226:229], v[234:237], v[50:65]
	ds_read_b128 v[174:177], v178 offset:9280
	v_mfma_f32_32x32x16_bf16 v[34:49], v[226:229], v[202:205], v[34:49]
	ds_read_b128 v[190:193], v178 offset:13888
	s_waitcnt lgkmcnt(6)
	v_mfma_f32_32x32x16_bf16 v[18:33], v[230:233], v[234:237], v[18:33]
	v_mfma_f32_32x32x16_bf16 v[2:17], v[230:233], v[202:205], v[2:17]
	s_waitcnt lgkmcnt(4)
	v_mfma_f32_32x32x16_bf16 v[114:129], v[166:169], v[194:197], v[114:129]
	ds_read_b128 v[234:237], v179 offset:36960
	s_waitcnt lgkmcnt(4)
	v_mfma_f32_32x32x16_bf16 v[98:113], v[166:169], v[198:201], v[98:113]
	ds_read_b128 v[218:221], v178 offset:96
	s_waitcnt lgkmcnt(4)
	v_mfma_f32_32x32x16_bf16 v[82:97], v[170:173], v[194:197], v[82:97]
	ds_read_b128 v[202:205], v179 offset:41568
	v_mfma_f32_32x32x16_bf16 v[66:81], v[170:173], v[198:201], v[66:81]
	ds_read_b128 v[222:225], v178 offset:4704
	s_waitcnt lgkmcnt(5)
	v_mfma_f32_32x32x16_bf16 v[50:65], v[174:177], v[194:197], v[50:65]
	ds_read_b128 v[226:229], v178 offset:9312
	v_mfma_f32_32x32x16_bf16 v[34:49], v[174:177], v[198:201], v[34:49]
	ds_read_b128 v[230:233], v178 offset:13920
	s_waitcnt lgkmcnt(6)
	v_mfma_f32_32x32x16_bf16 v[18:33], v[190:193], v[194:197], v[18:33]
	v_mfma_f32_32x32x16_bf16 v[2:17], v[190:193], v[198:201], v[2:17]
	s_waitcnt lgkmcnt(0)
; DI int crow(int reg, int h) { return (reg & 3) + 8 * (reg >> 2) + 4 * h; }
; template <typename Epi>
; DI void gemm_tile512(const u16* __restrict__ A, int lda, const u16* __restrict__ Bt, int ldb, int K, char* lds_all, Epi epi) {
;     ...
;     G5_COMPUTE(cur ^ 1);
;   }
; #pragma unroll 1
;   for (int half = 0; half < 2; ++half) {
;     __syncthreads();
;     if (wm == half) {
; #pragma unroll
;       for (int i = 0; i < 4; ++i)
; #pragma unroll
;         for (int j = 0; j < 2; ++j)
; #pragma unroll
;           for (int g = 0; g < 16; ++g) Cs[(i * 32 + crow(g, h)) * CSW + wn * 64 + j * 32 + r] = acc[i][j][g];
;     }
	v_mfma_f32_32x32x16_bf16 v[114:129], v[218:221], v[234:237], v[114:129]
	v_mfma_f32_32x32x16_bf16 v[98:113], v[218:221], v[202:205], v[98:113]
	v_mfma_f32_32x32x16_bf16 v[82:97], v[222:225], v[234:237], v[82:97]
	v_mfma_f32_32x32x16_bf16 v[66:81], v[222:225], v[202:205], v[66:81]
	v_mfma_f32_32x32x16_bf16 v[50:65], v[226:229], v[234:237], v[50:65]
	v_mfma_f32_32x32x16_bf16 v[34:49], v[226:229], v[202:205], v[34:49]
	v_mfma_f32_32x32x16_bf16 v[18:33], v[230:233], v[234:237], v[18:33]
	v_mfma_f32_32x32x16_bf16 v[2:17], v[230:233], v[202:205], v[2:17]
	v_mov_b32_e32 v190, 0x10c20
	v_mov_b32_e32 v191, 0x11040
	v_mov_b32_e32 v192, 0x11460
	v_mov_b32_e32 v193, 0x12900
	v_mov_b32_e32 v194, 0x12d20
	v_mov_b32_e32 v195, 0x13140
	v_mov_b32_e32 v196, 0x13560
	v_mov_b32_e32 v197, 0x14a00
	v_mov_b32_e32 v198, 0x14e20
	v_mov_b32_e32 v199, 0x15240
	v_mov_b32_e32 v200, 0x15660
	v_mov_b32_e32 v201, 0x16b00
	v_mov_b32_e32 v202, 0x16f20
	v_mov_b32_e32 v203, 0x17340
	v_mov_b32_e32 v204, 0x17760
	v_mov_b32_e32 v205, 0x18c00
	v_mov_b32_e32 v206, 0x19020
	v_mov_b32_e32 v207, 0x19440
	v_mov_b32_e32 v208, 0x10800
	v_lshrrev_b32_e32 v218, 8, v165
	v_bfe_u32 v219, v165, 5, 1
	v_and_b32_e32 v220, 31, v165
	v_bfe_u32 v221, v165, 6, 2
	s_mov_b32 s14, 0
	s_movk_i32 s10, 0x1080
	v_mov_b32_e32 v157, 0x1da60
	v_mad_u32_u24 v154, v219, s10, v245
	v_mad_u32_u24 v155, v219, s10, v246
	v_mad_u32_u24 v156, v219, s10, v247
	v_mad_u32_u24 v157, v219, s10, v157
	v_mov_b32_e32 v158, 0x1ef00
	v_mov_b32_e32 v159, 0x1f320
	v_mov_b32_e32 v160, 0x1f740
	v_mad_u32_u24 v158, v219, s10, v158
	v_mad_u32_u24 v159, v219, s10, v159
	v_mad_u32_u24 v160, v219, s10, v160
	v_lshlrev_b32_e32 v0, 8, v221
	v_mov_b32_e32 v166, 0x1fb60
	v_lshl_or_b32 v161, v220, 2, v0
	v_mad_u32_u24 v166, v219, s10, v166
	v_mad_u32_u24 v0, v219, s10, v161
	v_add_u32_e32 v154, v161, v154
	v_add_u32_e32 v155, v161, v155
	v_add_u32_e32 v156, v161, v156
	v_add_u32_e32 v157, v161, v157
	v_mad_u32_u24 v130, v219, s10, v208
	v_mad_u32_u24 v131, v219, s10, v190
	v_mad_u32_u24 v132, v219, s10, v191
	v_mad_u32_u24 v133, v219, s10, v192
	v_add_u32_e32 v130, v161, v130
	v_add_u32_e32 v131, v161, v131
	v_add_u32_e32 v132, v161, v132
	v_add_u32_e32 v133, v161, v133
	v_add_u32_e32 v158, v161, v158
	v_add_u32_e32 v159, v161, v159
	v_add_u32_e32 v160, v161, v160
	v_mad_u32_u24 v134, v219, s10, v193
	v_mad_u32_u24 v135, v219, s10, v194
	v_mad_u32_u24 v136, v219, s10, v195
	v_mad_u32_u24 v137, v219, s10, v196
	v_add_u32_e32 v134, v161, v134
	v_add_u32_e32 v135, v161, v135
	v_add_u32_e32 v136, v161, v136
	v_add_u32_e32 v137, v161, v137
	v_mad_u32_u24 v138, v219, s10, v197
	v_mad_u32_u24 v139, v219, s10, v198
	v_mad_u32_u24 v140, v219, s10, v199
	v_mad_u32_u24 v141, v219, s10, v200
	v_add_u32_e32 v138, v161, v138
	v_add_u32_e32 v139, v161, v139
	v_add_u32_e32 v140, v161, v140
	v_mad_u32_u24 v146, v219, s10, v205
	v_mad_u32_u24 v147, v219, s10, v206
	v_mad_u32_u24 v148, v219, s10, v207
	v_mad_u32_u24 v149, v219, s10, v240
	v_add_u32_e32 v141, v161, v141
	v_add_u32_e32 v146, v161, v146
	v_add_u32_e32 v147, v161, v147
	v_mad_u32_u24 v142, v219, s10, v201
	v_mad_u32_u24 v143, v219, s10, v202
	v_mad_u32_u24 v144, v219, s10, v203
	v_mad_u32_u24 v145, v219, s10, v204
	v_mad_u32_u24 v150, v219, s10, v241
	v_mad_u32_u24 v151, v219, s10, v242
	v_mad_u32_u24 v152, v219, s10, v243
	v_mad_u32_u24 v153, v219, s10, v244
	s_mov_b64 s[10:11], -1
	v_add_u32_e32 v142, v161, v142
	v_add_u32_e32 v143, v161, v143
	v_add_u32_e32 v144, v161, v144
	v_add_u32_e32 v145, v161, v145
	v_add_u32_e32 v148, v161, v148
	v_add_u32_e32 v149, v161, v149
	v_add_u32_e32 v150, v161, v150
	v_add_u32_e32 v151, v161, v151
	v_add_u32_e32 v152, v161, v152
	v_add_u32_e32 v153, v161, v153
	v_add_u32_e32 v161, v161, v166
	s_branch .LBB0_856
